# K-loop MFMA segments: the redundant counted lgkmcnt waits between MFMAs and the mid-segment setprio 0/1 pair removed (32 bare MFMAs per segment)
# baseline (speedup 1.0000x reference)
.Lnb_p1:
	s_add_i32 s7, s4, 0xfff84000
	s_cmp_eq_u32 s6, 28
	s_cselect_b32 s17, s0, s7
	s_cselect_b32 s16, s1, s5
	s_or_b32 s7, s17, 0x4000
	s_mov_b32 m0, s79
	s_nop 0
	buffer_load_dwordx4 v242, s[24:27], s4 offen lds
	s_nop 0
	s_mov_b32 m0, s83
	s_nop 0
	buffer_load_dwordx4 v243, s[24:27], s4 offen lds
	s_waitcnt vmcnt(24)
	s_waitcnt lgkmcnt(0)
	s_barrier
	s_setprio 1
	v_mfma_f32_16x16x32_bf16 v[180:183], v[16:19], v[192:195], 0
	v_mfma_f32_16x16x32_bf16 v[164:167], v[24:27], v[192:195], 0
	v_mfma_f32_16x16x32_bf16 v[148:151], v[16:19], v[200:203], 0
	v_mfma_f32_16x16x32_bf16 v[140:143], v[24:27], v[200:203], 0
	v_mfma_f32_16x16x32_bf16 v[132:135], v[16:19], v[220:223], 0
	v_mfma_f32_16x16x32_bf16 v[124:127], v[24:27], v[220:223], 0
	v_mfma_f32_16x16x32_bf16 v[116:119], v[16:19], v[228:231], 0
	v_mfma_f32_16x16x32_bf16 v[108:111], v[24:27], v[228:231], 0
	v_mfma_f32_16x16x32_bf16 v[180:183], v[20:23], v[196:199], v[180:183]
	v_mfma_f32_16x16x32_bf16 v[164:167], v[28:31], v[196:199], v[164:167]
	v_mfma_f32_16x16x32_bf16 v[148:151], v[20:23], v[204:207], v[148:151]
	v_mfma_f32_16x16x32_bf16 v[140:143], v[28:31], v[204:207], v[140:143]
	v_mfma_f32_16x16x32_bf16 v[132:135], v[20:23], v[224:227], v[132:135]
	v_mfma_f32_16x16x32_bf16 v[124:127], v[28:31], v[224:227], v[124:127]
	v_mfma_f32_16x16x32_bf16 v[116:119], v[20:23], v[246:249], v[116:119]
	v_mfma_f32_16x16x32_bf16 v[108:111], v[28:31], v[246:249], v[108:111]
	v_mfma_f32_16x16x32_bf16 v[172:175], v[152:155], v[192:195], 0
	v_mfma_f32_16x16x32_bf16 v[156:159], v[168:171], v[192:195], 0
	v_mfma_f32_16x16x32_bf16 v[144:147], v[152:155], v[200:203], 0
	v_mfma_f32_16x16x32_bf16 v[136:139], v[168:171], v[200:203], 0
	v_mfma_f32_16x16x32_bf16 v[128:131], v[152:155], v[220:223], 0
	v_mfma_f32_16x16x32_bf16 v[120:123], v[168:171], v[220:223], 0
	v_mfma_f32_16x16x32_bf16 v[112:115], v[152:155], v[228:231], 0
	v_mfma_f32_16x16x32_bf16 v[104:107], v[168:171], v[228:231], 0
	v_mfma_f32_16x16x32_bf16 v[172:175], v[160:163], v[196:199], v[172:175]
	v_mfma_f32_16x16x32_bf16 v[156:159], v[176:179], v[196:199], v[156:159]
	v_mfma_f32_16x16x32_bf16 v[144:147], v[160:163], v[204:207], v[144:147]
	v_mfma_f32_16x16x32_bf16 v[136:139], v[176:179], v[204:207], v[136:139]
	v_mfma_f32_16x16x32_bf16 v[128:131], v[160:163], v[224:227], v[128:131]
	v_mfma_f32_16x16x32_bf16 v[120:123], v[176:179], v[224:227], v[120:123]
	v_mfma_f32_16x16x32_bf16 v[112:115], v[160:163], v[246:249], v[112:115]
	v_mfma_f32_16x16x32_bf16 v[104:107], v[176:179], v[246:249], v[104:107]
	s_setprio 0
	s_barrier
	ds_read_b128 v[192:195], v245 offset:16384
	ds_read_b128 v[196:199], v245 offset:17408
	ds_read_b128 v[200:203], v245 offset:18432
	ds_read_b128 v[204:207], v245 offset:19456
	ds_read_b128 v[220:223], v245 offset:20480
	ds_read_b128 v[224:227], v245 offset:21504
	ds_read_b128 v[228:231], v245 offset:22528
	ds_read_b128 v[246:249], v245 offset:23552
	s_mov_b32 m0, s51
	s_nop 0
	buffer_load_dwordx4 v242, s[56:59], s16 offen lds
	s_add_i32 s18, s16, 0x80000
	s_mov_b32 m0, s52
	s_nop 0
	buffer_load_dwordx4 v243, s[56:59], s16 offen lds
	s_nop 0
	s_mov_b32 m0, s53
	s_nop 0
	buffer_load_dwordx4 v242, s[56:59], s18 offen lds
	s_nop 0
	s_mov_b32 m0, s55
	s_nop 0
	buffer_load_dwordx4 v243, s[56:59], s18 offen lds
	s_nop 0
	s_mov_b32 m0, s31
	s_nop 0
	buffer_load_dwordx4 v242, s[24:27], s17 offen lds
	s_nop 0
	s_mov_b32 m0, s68
	s_nop 0
	buffer_load_dwordx4 v243, s[24:27], s17 offen lds
	s_waitcnt vmcnt(24)
	s_waitcnt lgkmcnt(0)
	s_barrier
	s_setprio 1
	v_mfma_f32_16x16x32_bf16 v[76:79], v[16:19], v[192:195], 0
	v_mfma_f32_16x16x32_bf16 v[68:71], v[24:27], v[192:195], 0
	v_mfma_f32_16x16x32_bf16 v[60:63], v[16:19], v[200:203], 0
	v_mfma_f32_16x16x32_bf16 v[52:55], v[24:27], v[200:203], 0
	v_mfma_f32_16x16x32_bf16 v[44:47], v[16:19], v[220:223], 0
	v_mfma_f32_16x16x32_bf16 v[36:39], v[24:27], v[220:223], 0
	v_mfma_f32_16x16x32_bf16 v[12:15], v[16:19], v[228:231], 0
	v_mfma_f32_16x16x32_bf16 v[4:7], v[24:27], v[228:231], 0
	v_mfma_f32_16x16x32_bf16 v[76:79], v[20:23], v[196:199], v[76:79]
	v_mfma_f32_16x16x32_bf16 v[68:71], v[28:31], v[196:199], v[68:71]
	v_mfma_f32_16x16x32_bf16 v[60:63], v[20:23], v[204:207], v[60:63]
	v_mfma_f32_16x16x32_bf16 v[52:55], v[28:31], v[204:207], v[52:55]
	v_mfma_f32_16x16x32_bf16 v[44:47], v[20:23], v[224:227], v[44:47]
	v_mfma_f32_16x16x32_bf16 v[36:39], v[28:31], v[224:227], v[36:39]
	v_mfma_f32_16x16x32_bf16 v[12:15], v[20:23], v[246:249], v[12:15]
	v_mfma_f32_16x16x32_bf16 v[4:7], v[28:31], v[246:249], v[4:7]
	v_mfma_f32_16x16x32_bf16 v[40:43], v[152:155], v[220:223], 0
	v_mfma_f32_16x16x32_bf16 v[32:35], v[168:171], v[220:223], 0
	v_mfma_f32_16x16x32_bf16 v[8:11], v[152:155], v[228:231], 0
	v_mfma_f32_16x16x32_bf16 v[0:3], v[168:171], v[228:231], 0
	v_mfma_f32_16x16x32_bf16 v[16:19], v[152:155], v[192:195], 0
	v_mfma_f32_16x16x32_bf16 v[20:23], v[168:171], v[192:195], 0
	v_mfma_f32_16x16x32_bf16 v[24:27], v[152:155], v[200:203], 0
	v_mfma_f32_16x16x32_bf16 v[28:31], v[168:171], v[200:203], 0
	v_mfma_f32_16x16x32_bf16 v[40:43], v[160:163], v[224:227], v[40:43]
	v_mfma_f32_16x16x32_bf16 v[32:35], v[176:179], v[224:227], v[32:35]
	v_mfma_f32_16x16x32_bf16 v[8:11], v[160:163], v[246:249], v[8:11]
	v_mfma_f32_16x16x32_bf16 v[0:3], v[176:179], v[246:249], v[0:3]
	v_mfma_f32_16x16x32_bf16 v[16:19], v[160:163], v[196:199], v[16:19]
	v_mfma_f32_16x16x32_bf16 v[20:23], v[176:179], v[196:199], v[20:23]
	v_mfma_f32_16x16x32_bf16 v[24:27], v[160:163], v[204:207], v[24:27]
	v_mfma_f32_16x16x32_bf16 v[28:31], v[176:179], v[204:207], v[28:31]
	s_setprio 0
	s_barrier
	v_add_u32_e32 v72, 0x18000, v83
	v_add_u32_e32 v80, 0x1c000, v83
	ds_read_b128 v[48:51], v72
	ds_read_b128 v[56:59], v72 offset:1024
	ds_read_b128 v[64:67], v72 offset:2048
	ds_read_b128 v[72:75], v72 offset:3072
	ds_read_b128 v[152:155], v80
	ds_read_b128 v[160:163], v80 offset:1024
	ds_read_b128 v[168:171], v80 offset:2048
	ds_read_b128 v[176:179], v80 offset:3072
	ds_read_b128 v[192:195], v245 offset:32768
	ds_read_b128 v[196:199], v245 offset:33792
	ds_read_b128 v[200:203], v245 offset:34816
	ds_read_b128 v[204:207], v245 offset:35840
	ds_read_b128 v[220:223], v245 offset:36864
	ds_read_b128 v[224:227], v245 offset:37888
	ds_read_b128 v[228:231], v245 offset:38912
	ds_read_b128 v[246:249], v245 offset:39936
	s_add_i32 s17, s17, 0x80000
	s_mov_b32 m0, s69
	s_nop 0
	buffer_load_dwordx4 v242, s[24:27], s17 offen lds
	s_nop 0
	s_mov_b32 m0, s70
	s_nop 0
	buffer_load_dwordx4 v243, s[24:27], s17 offen lds
	s_waitcnt vmcnt(8)
	s_waitcnt lgkmcnt(0)
	s_barrier
	s_setprio 1
	v_mfma_f32_16x16x32_bf16 v[180:183], v[48:51], v[192:195], v[180:183]
	v_mfma_f32_16x16x32_bf16 v[164:167], v[64:67], v[192:195], v[164:167]
	v_mfma_f32_16x16x32_bf16 v[148:151], v[48:51], v[200:203], v[148:151]
	v_mfma_f32_16x16x32_bf16 v[140:143], v[64:67], v[200:203], v[140:143]
	v_mfma_f32_16x16x32_bf16 v[132:135], v[48:51], v[220:223], v[132:135]
	v_mfma_f32_16x16x32_bf16 v[124:127], v[64:67], v[220:223], v[124:127]
	v_mfma_f32_16x16x32_bf16 v[116:119], v[48:51], v[228:231], v[116:119]
	v_mfma_f32_16x16x32_bf16 v[108:111], v[64:67], v[228:231], v[108:111]
	v_mfma_f32_16x16x32_bf16 v[180:183], v[56:59], v[196:199], v[180:183]
	v_mfma_f32_16x16x32_bf16 v[164:167], v[72:75], v[196:199], v[164:167]
	v_mfma_f32_16x16x32_bf16 v[148:151], v[56:59], v[204:207], v[148:151]
	v_mfma_f32_16x16x32_bf16 v[140:143], v[72:75], v[204:207], v[140:143]
	v_mfma_f32_16x16x32_bf16 v[132:135], v[56:59], v[224:227], v[132:135]
	v_mfma_f32_16x16x32_bf16 v[124:127], v[72:75], v[224:227], v[124:127]
	v_mfma_f32_16x16x32_bf16 v[116:119], v[56:59], v[246:249], v[116:119]
	v_mfma_f32_16x16x32_bf16 v[108:111], v[72:75], v[246:249], v[108:111]
	v_mfma_f32_16x16x32_bf16 v[172:175], v[152:155], v[192:195], v[172:175]
	v_mfma_f32_16x16x32_bf16 v[156:159], v[168:171], v[192:195], v[156:159]
	v_mfma_f32_16x16x32_bf16 v[144:147], v[152:155], v[200:203], v[144:147]
	v_mfma_f32_16x16x32_bf16 v[136:139], v[168:171], v[200:203], v[136:139]
	v_mfma_f32_16x16x32_bf16 v[128:131], v[152:155], v[220:223], v[128:131]
	v_mfma_f32_16x16x32_bf16 v[120:123], v[168:171], v[220:223], v[120:123]
	v_mfma_f32_16x16x32_bf16 v[112:115], v[152:155], v[228:231], v[112:115]
	v_mfma_f32_16x16x32_bf16 v[104:107], v[168:171], v[228:231], v[104:107]
	v_mfma_f32_16x16x32_bf16 v[172:175], v[160:163], v[196:199], v[172:175]
	v_mfma_f32_16x16x32_bf16 v[156:159], v[176:179], v[196:199], v[156:159]
	v_mfma_f32_16x16x32_bf16 v[144:147], v[160:163], v[204:207], v[144:147]
	v_mfma_f32_16x16x32_bf16 v[136:139], v[176:179], v[204:207], v[136:139]
	v_mfma_f32_16x16x32_bf16 v[128:131], v[160:163], v[224:227], v[128:131]
	v_mfma_f32_16x16x32_bf16 v[120:123], v[176:179], v[224:227], v[120:123]
	v_mfma_f32_16x16x32_bf16 v[112:115], v[160:163], v[246:249], v[112:115]
	v_mfma_f32_16x16x32_bf16 v[104:107], v[176:179], v[246:249], v[104:107]
	s_setprio 0
	s_barrier
	ds_read_b128 v[192:195], v245 offset:49152
	ds_read_b128 v[196:199], v245 offset:50176
	ds_read_b128 v[200:203], v245 offset:51200
	ds_read_b128 v[204:207], v245 offset:52224
	ds_read_b128 v[220:223], v245 offset:53248
	ds_read_b128 v[224:227], v245 offset:54272
	ds_read_b128 v[228:231], v245 offset:55296
	ds_read_b128 v[246:249], v245 offset:56320
	s_or_b32 s17, s16, 0x4000
	s_mov_b32 m0, s73
	s_nop 0
	buffer_load_dwordx4 v242, s[56:59], s17 offen lds
	s_add_i32 s16, s16, 0x84000
	s_mov_b32 m0, s74
	s_nop 0
	buffer_load_dwordx4 v243, s[56:59], s17 offen lds
	s_nop 0
	s_mov_b32 m0, s77
	s_nop 0
	buffer_load_dwordx4 v242, s[56:59], s16 offen lds
	s_nop 0
	s_mov_b32 m0, s78
	s_nop 0
	buffer_load_dwordx4 v243, s[56:59], s16 offen lds
	s_nop 0
	s_mov_b32 m0, s75
	s_nop 0
	buffer_load_dwordx4 v242, s[24:27], s7 offen lds
	s_nop 0
	s_mov_b32 m0, s76
	s_nop 0
	buffer_load_dwordx4 v243, s[24:27], s7 offen lds
	s_waitcnt vmcnt(8)
	s_waitcnt lgkmcnt(0)
	s_barrier
	s_setprio 1
	v_mfma_f32_16x16x32_bf16 v[76:79], v[48:51], v[192:195], v[76:79]
	v_mfma_f32_16x16x32_bf16 v[68:71], v[64:67], v[192:195], v[68:71]
	v_mfma_f32_16x16x32_bf16 v[60:63], v[48:51], v[200:203], v[60:63]
	v_mfma_f32_16x16x32_bf16 v[52:55], v[64:67], v[200:203], v[52:55]
	v_mfma_f32_16x16x32_bf16 v[44:47], v[48:51], v[220:223], v[44:47]
	v_mfma_f32_16x16x32_bf16 v[36:39], v[64:67], v[220:223], v[36:39]
	v_mfma_f32_16x16x32_bf16 v[12:15], v[48:51], v[228:231], v[12:15]
	v_mfma_f32_16x16x32_bf16 v[4:7], v[64:67], v[228:231], v[4:7]
	v_mfma_f32_16x16x32_bf16 v[76:79], v[56:59], v[196:199], v[76:79]
	v_mfma_f32_16x16x32_bf16 v[68:71], v[72:75], v[196:199], v[68:71]
	v_mfma_f32_16x16x32_bf16 v[60:63], v[56:59], v[204:207], v[60:63]
	v_mfma_f32_16x16x32_bf16 v[52:55], v[72:75], v[204:207], v[52:55]
	v_mfma_f32_16x16x32_bf16 v[44:47], v[56:59], v[224:227], v[44:47]
	v_mfma_f32_16x16x32_bf16 v[36:39], v[72:75], v[224:227], v[36:39]
	v_mfma_f32_16x16x32_bf16 v[12:15], v[56:59], v[246:249], v[12:15]
	v_mfma_f32_16x16x32_bf16 v[4:7], v[72:75], v[246:249], v[4:7]
	v_mfma_f32_16x16x32_bf16 v[16:19], v[152:155], v[192:195], v[16:19]
	v_mfma_f32_16x16x32_bf16 v[72:75], v[160:163], v[196:199], v[16:19]
	v_mfma_f32_16x16x32_bf16 v[16:19], v[168:171], v[192:195], v[20:23]
	v_mfma_f32_16x16x32_bf16 v[64:67], v[176:179], v[196:199], v[16:19]
	v_mfma_f32_16x16x32_bf16 v[16:19], v[152:155], v[200:203], v[24:27]
	v_mfma_f32_16x16x32_bf16 v[56:59], v[160:163], v[204:207], v[16:19]
	v_mfma_f32_16x16x32_bf16 v[16:19], v[168:171], v[200:203], v[28:31]
	v_mfma_f32_16x16x32_bf16 v[48:51], v[176:179], v[204:207], v[16:19]
	v_mfma_f32_16x16x32_bf16 v[16:19], v[152:155], v[220:223], v[40:43]
	v_mfma_f32_16x16x32_bf16 v[40:43], v[160:163], v[224:227], v[16:19]
	v_mfma_f32_16x16x32_bf16 v[16:19], v[168:171], v[220:223], v[32:35]
	v_mfma_f32_16x16x32_bf16 v[8:11], v[152:155], v[228:231], v[8:11]
	v_mfma_f32_16x16x32_bf16 v[0:3], v[168:171], v[228:231], v[0:3]
	v_mfma_f32_16x16x32_bf16 v[32:35], v[176:179], v[224:227], v[16:19]
	v_mfma_f32_16x16x32_bf16 v[8:11], v[160:163], v[246:249], v[8:11]
	v_mfma_f32_16x16x32_bf16 v[0:3], v[176:179], v[246:249], v[0:3]
	s_setprio 0
	s_barrier
	s_add_i32 s6, s6, 2
	s_add_i32 s4, s4, 0x8000
	s_add_i32 s5, s5, 0x8000
.LBB0_143:
	v_add_u32_e32 v28, 0x10000, v83
	v_add_u32_e32 v80, 0x14000, v83
	ds_read_b128 v[16:19], v28
	ds_read_b128 v[20:23], v28 offset:1024
	ds_read_b128 v[24:27], v28 offset:2048
	ds_read_b128 v[28:31], v28 offset:3072
	ds_read_b128 v[152:155], v80
	ds_read_b128 v[160:163], v80 offset:1024
	ds_read_b128 v[168:171], v80 offset:2048
	ds_read_b128 v[176:179], v80 offset:3072
	s_add_i32 s7, s4, 0xfff84000
	s_cmp_eq_u32 s6, 28
	s_cselect_b32 s17, s0, s7
	s_cselect_b32 s16, s1, s5
	s_or_b32 s7, s17, 0x4000
	ds_read_b128 v[192:195], v245
	ds_read_b128 v[196:199], v245 offset:1024
	ds_read_b128 v[200:203], v245 offset:2048
	ds_read_b128 v[204:207], v245 offset:3072
	ds_read_b128 v[220:223], v245 offset:4096
	ds_read_b128 v[224:227], v245 offset:5120
	ds_read_b128 v[228:231], v245 offset:6144
	ds_read_b128 v[246:249], v245 offset:7168
	s_mov_b32 m0, s79
	s_nop 0
	buffer_load_dwordx4 v242, s[24:27], s4 offen lds
	s_nop 0
	s_mov_b32 m0, s83
	s_nop 0
	buffer_load_dwordx4 v243, s[24:27], s4 offen lds
	s_waitcnt vmcnt(8)
	s_waitcnt lgkmcnt(0)
	s_barrier
	s_setprio 1
	v_mfma_f32_16x16x32_bf16 v[180:183], v[16:19], v[192:195], v[180:183]
	v_mfma_f32_16x16x32_bf16 v[164:167], v[24:27], v[192:195], v[164:167]
	v_mfma_f32_16x16x32_bf16 v[148:151], v[16:19], v[200:203], v[148:151]
	v_mfma_f32_16x16x32_bf16 v[140:143], v[24:27], v[200:203], v[140:143]
	v_mfma_f32_16x16x32_bf16 v[132:135], v[16:19], v[220:223], v[132:135]
	v_mfma_f32_16x16x32_bf16 v[124:127], v[24:27], v[220:223], v[124:127]
	v_mfma_f32_16x16x32_bf16 v[116:119], v[16:19], v[228:231], v[116:119]
	v_mfma_f32_16x16x32_bf16 v[108:111], v[24:27], v[228:231], v[108:111]
	v_mfma_f32_16x16x32_bf16 v[180:183], v[20:23], v[196:199], v[180:183]
	v_mfma_f32_16x16x32_bf16 v[164:167], v[28:31], v[196:199], v[164:167]
	v_mfma_f32_16x16x32_bf16 v[148:151], v[20:23], v[204:207], v[148:151]
	v_mfma_f32_16x16x32_bf16 v[140:143], v[28:31], v[204:207], v[140:143]
	v_mfma_f32_16x16x32_bf16 v[132:135], v[20:23], v[224:227], v[132:135]
	v_mfma_f32_16x16x32_bf16 v[124:127], v[28:31], v[224:227], v[124:127]
	v_mfma_f32_16x16x32_bf16 v[116:119], v[20:23], v[246:249], v[116:119]
	v_mfma_f32_16x16x32_bf16 v[108:111], v[28:31], v[246:249], v[108:111]
	v_mfma_f32_16x16x32_bf16 v[172:175], v[152:155], v[192:195], v[172:175]
	v_mfma_f32_16x16x32_bf16 v[156:159], v[168:171], v[192:195], v[156:159]
	v_mfma_f32_16x16x32_bf16 v[144:147], v[152:155], v[200:203], v[144:147]
	v_mfma_f32_16x16x32_bf16 v[136:139], v[168:171], v[200:203], v[136:139]
	v_mfma_f32_16x16x32_bf16 v[128:131], v[152:155], v[220:223], v[128:131]
	v_mfma_f32_16x16x32_bf16 v[120:123], v[168:171], v[220:223], v[120:123]
	v_mfma_f32_16x16x32_bf16 v[112:115], v[152:155], v[228:231], v[112:115]
	v_mfma_f32_16x16x32_bf16 v[104:107], v[168:171], v[228:231], v[104:107]
	v_mfma_f32_16x16x32_bf16 v[172:175], v[160:163], v[196:199], v[172:175]
	v_mfma_f32_16x16x32_bf16 v[156:159], v[176:179], v[196:199], v[156:159]
	v_mfma_f32_16x16x32_bf16 v[144:147], v[160:163], v[204:207], v[144:147]
	v_mfma_f32_16x16x32_bf16 v[136:139], v[176:179], v[204:207], v[136:139]
	v_mfma_f32_16x16x32_bf16 v[128:131], v[160:163], v[224:227], v[128:131]
	v_mfma_f32_16x16x32_bf16 v[120:123], v[176:179], v[224:227], v[120:123]
	v_mfma_f32_16x16x32_bf16 v[112:115], v[160:163], v[246:249], v[112:115]
	v_mfma_f32_16x16x32_bf16 v[104:107], v[176:179], v[246:249], v[104:107]
	s_setprio 0
	s_barrier
	ds_read_b128 v[192:195], v245 offset:16384
	ds_read_b128 v[196:199], v245 offset:17408
	ds_read_b128 v[200:203], v245 offset:18432
	ds_read_b128 v[204:207], v245 offset:19456
	ds_read_b128 v[220:223], v245 offset:20480
	ds_read_b128 v[224:227], v245 offset:21504
	ds_read_b128 v[228:231], v245 offset:22528
	ds_read_b128 v[246:249], v245 offset:23552
	s_mov_b32 m0, s51
	s_nop 0
	buffer_load_dwordx4 v242, s[56:59], s16 offen lds
	s_add_i32 s18, s16, 0x80000
	s_mov_b32 m0, s52
	s_nop 0
	buffer_load_dwordx4 v243, s[56:59], s16 offen lds
	s_nop 0
	s_mov_b32 m0, s53
	s_nop 0
	buffer_load_dwordx4 v242, s[56:59], s18 offen lds
	s_nop 0
	s_mov_b32 m0, s55
	s_nop 0
	buffer_load_dwordx4 v243, s[56:59], s18 offen lds
	s_nop 0
	s_mov_b32 m0, s31
	s_nop 0
	buffer_load_dwordx4 v242, s[24:27], s17 offen lds
	s_nop 0
	s_mov_b32 m0, s68
	s_nop 0
	buffer_load_dwordx4 v243, s[24:27], s17 offen lds
	s_waitcnt vmcnt(8)
	s_waitcnt lgkmcnt(0)
	s_barrier
	s_setprio 1
	v_mfma_f32_16x16x32_bf16 v[76:79], v[16:19], v[192:195], v[76:79]
	v_mfma_f32_16x16x32_bf16 v[68:71], v[24:27], v[192:195], v[68:71]
	v_mfma_f32_16x16x32_bf16 v[60:63], v[16:19], v[200:203], v[60:63]
	v_mfma_f32_16x16x32_bf16 v[52:55], v[24:27], v[200:203], v[52:55]
	v_mfma_f32_16x16x32_bf16 v[44:47], v[16:19], v[220:223], v[44:47]
	v_mfma_f32_16x16x32_bf16 v[36:39], v[24:27], v[220:223], v[36:39]
	v_mfma_f32_16x16x32_bf16 v[12:15], v[16:19], v[228:231], v[12:15]
	v_mfma_f32_16x16x32_bf16 v[4:7], v[24:27], v[228:231], v[4:7]
	v_mfma_f32_16x16x32_bf16 v[76:79], v[20:23], v[196:199], v[76:79]
	v_mfma_f32_16x16x32_bf16 v[68:71], v[28:31], v[196:199], v[68:71]
	v_mfma_f32_16x16x32_bf16 v[60:63], v[20:23], v[204:207], v[60:63]
	v_mfma_f32_16x16x32_bf16 v[52:55], v[28:31], v[204:207], v[52:55]
	v_mfma_f32_16x16x32_bf16 v[44:47], v[20:23], v[224:227], v[44:47]
	v_mfma_f32_16x16x32_bf16 v[36:39], v[28:31], v[224:227], v[36:39]
	v_mfma_f32_16x16x32_bf16 v[12:15], v[20:23], v[246:249], v[12:15]
	v_mfma_f32_16x16x32_bf16 v[4:7], v[28:31], v[246:249], v[4:7]
	v_mfma_f32_16x16x32_bf16 v[40:43], v[152:155], v[220:223], v[40:43]
	v_mfma_f32_16x16x32_bf16 v[32:35], v[168:171], v[220:223], v[32:35]
	v_mfma_f32_16x16x32_bf16 v[8:11], v[152:155], v[228:231], v[8:11]
	v_mfma_f32_16x16x32_bf16 v[0:3], v[168:171], v[228:231], v[0:3]
	v_mfma_f32_16x16x32_bf16 v[16:19], v[152:155], v[192:195], v[72:75]
	v_mfma_f32_16x16x32_bf16 v[20:23], v[168:171], v[192:195], v[64:67]
	v_mfma_f32_16x16x32_bf16 v[24:27], v[152:155], v[200:203], v[56:59]
	v_mfma_f32_16x16x32_bf16 v[28:31], v[168:171], v[200:203], v[48:51]
	v_mfma_f32_16x16x32_bf16 v[40:43], v[160:163], v[224:227], v[40:43]
	v_mfma_f32_16x16x32_bf16 v[32:35], v[176:179], v[224:227], v[32:35]
	v_mfma_f32_16x16x32_bf16 v[8:11], v[160:163], v[246:249], v[8:11]
	v_mfma_f32_16x16x32_bf16 v[0:3], v[176:179], v[246:249], v[0:3]
	v_mfma_f32_16x16x32_bf16 v[16:19], v[160:163], v[196:199], v[16:19]
	v_mfma_f32_16x16x32_bf16 v[20:23], v[176:179], v[196:199], v[20:23]
	v_mfma_f32_16x16x32_bf16 v[24:27], v[160:163], v[204:207], v[24:27]
	v_mfma_f32_16x16x32_bf16 v[28:31], v[176:179], v[204:207], v[28:31]
	s_setprio 0
	s_barrier
	v_add_u32_e32 v72, 0x18000, v83
	v_add_u32_e32 v80, 0x1c000, v83
	ds_read_b128 v[48:51], v72
	ds_read_b128 v[56:59], v72 offset:1024
	ds_read_b128 v[64:67], v72 offset:2048
	ds_read_b128 v[72:75], v72 offset:3072
	ds_read_b128 v[152:155], v80
	ds_read_b128 v[160:163], v80 offset:1024
	ds_read_b128 v[168:171], v80 offset:2048
	ds_read_b128 v[176:179], v80 offset:3072
	ds_read_b128 v[192:195], v245 offset:32768
	ds_read_b128 v[196:199], v245 offset:33792
	ds_read_b128 v[200:203], v245 offset:34816
	ds_read_b128 v[204:207], v245 offset:35840
	ds_read_b128 v[220:223], v245 offset:36864
	ds_read_b128 v[224:227], v245 offset:37888
	ds_read_b128 v[228:231], v245 offset:38912
	ds_read_b128 v[246:249], v245 offset:39936
	s_add_i32 s17, s17, 0x80000
	s_mov_b32 m0, s69
	s_nop 0
	buffer_load_dwordx4 v242, s[24:27], s17 offen lds
	s_nop 0
	s_mov_b32 m0, s70
	s_nop 0
	buffer_load_dwordx4 v243, s[24:27], s17 offen lds
	s_waitcnt vmcnt(8)
	s_waitcnt lgkmcnt(0)
	s_barrier
	s_setprio 1
	v_mfma_f32_16x16x32_bf16 v[180:183], v[48:51], v[192:195], v[180:183]
	v_mfma_f32_16x16x32_bf16 v[164:167], v[64:67], v[192:195], v[164:167]
	v_mfma_f32_16x16x32_bf16 v[148:151], v[48:51], v[200:203], v[148:151]
	v_mfma_f32_16x16x32_bf16 v[140:143], v[64:67], v[200:203], v[140:143]
	v_mfma_f32_16x16x32_bf16 v[132:135], v[48:51], v[220:223], v[132:135]
	v_mfma_f32_16x16x32_bf16 v[124:127], v[64:67], v[220:223], v[124:127]
	v_mfma_f32_16x16x32_bf16 v[116:119], v[48:51], v[228:231], v[116:119]
	v_mfma_f32_16x16x32_bf16 v[108:111], v[64:67], v[228:231], v[108:111]
	v_mfma_f32_16x16x32_bf16 v[180:183], v[56:59], v[196:199], v[180:183]
	v_mfma_f32_16x16x32_bf16 v[164:167], v[72:75], v[196:199], v[164:167]
	v_mfma_f32_16x16x32_bf16 v[148:151], v[56:59], v[204:207], v[148:151]
	v_mfma_f32_16x16x32_bf16 v[140:143], v[72:75], v[204:207], v[140:143]
	v_mfma_f32_16x16x32_bf16 v[132:135], v[56:59], v[224:227], v[132:135]
	v_mfma_f32_16x16x32_bf16 v[124:127], v[72:75], v[224:227], v[124:127]
	v_mfma_f32_16x16x32_bf16 v[116:119], v[56:59], v[246:249], v[116:119]
	v_mfma_f32_16x16x32_bf16 v[108:111], v[72:75], v[246:249], v[108:111]
	v_mfma_f32_16x16x32_bf16 v[172:175], v[152:155], v[192:195], v[172:175]
	v_mfma_f32_16x16x32_bf16 v[156:159], v[168:171], v[192:195], v[156:159]
	v_mfma_f32_16x16x32_bf16 v[144:147], v[152:155], v[200:203], v[144:147]
	v_mfma_f32_16x16x32_bf16 v[136:139], v[168:171], v[200:203], v[136:139]
	v_mfma_f32_16x16x32_bf16 v[128:131], v[152:155], v[220:223], v[128:131]
	v_mfma_f32_16x16x32_bf16 v[120:123], v[168:171], v[220:223], v[120:123]
	v_mfma_f32_16x16x32_bf16 v[112:115], v[152:155], v[228:231], v[112:115]
	v_mfma_f32_16x16x32_bf16 v[104:107], v[168:171], v[228:231], v[104:107]
	v_mfma_f32_16x16x32_bf16 v[172:175], v[160:163], v[196:199], v[172:175]
	v_mfma_f32_16x16x32_bf16 v[156:159], v[176:179], v[196:199], v[156:159]
	v_mfma_f32_16x16x32_bf16 v[144:147], v[160:163], v[204:207], v[144:147]
	v_mfma_f32_16x16x32_bf16 v[136:139], v[176:179], v[204:207], v[136:139]
	v_mfma_f32_16x16x32_bf16 v[128:131], v[160:163], v[224:227], v[128:131]
	v_mfma_f32_16x16x32_bf16 v[120:123], v[176:179], v[224:227], v[120:123]
	v_mfma_f32_16x16x32_bf16 v[112:115], v[160:163], v[246:249], v[112:115]
	v_mfma_f32_16x16x32_bf16 v[104:107], v[176:179], v[246:249], v[104:107]
	s_setprio 0
	s_barrier
	ds_read_b128 v[192:195], v245 offset:49152
	ds_read_b128 v[196:199], v245 offset:50176
	ds_read_b128 v[200:203], v245 offset:51200
	ds_read_b128 v[204:207], v245 offset:52224
	ds_read_b128 v[220:223], v245 offset:53248
	ds_read_b128 v[224:227], v245 offset:54272
	ds_read_b128 v[228:231], v245 offset:55296
	ds_read_b128 v[246:249], v245 offset:56320
	s_or_b32 s17, s16, 0x4000
	s_mov_b32 m0, s73
	s_nop 0
	buffer_load_dwordx4 v242, s[56:59], s17 offen lds
	s_add_i32 s16, s16, 0x84000
	s_mov_b32 m0, s74
	s_nop 0
	buffer_load_dwordx4 v243, s[56:59], s17 offen lds
	s_nop 0
	s_mov_b32 m0, s77
	s_nop 0
	buffer_load_dwordx4 v242, s[56:59], s16 offen lds
	s_nop 0
	s_mov_b32 m0, s78
	s_nop 0
	buffer_load_dwordx4 v243, s[56:59], s16 offen lds
	s_nop 0
	s_mov_b32 m0, s75
	s_nop 0
	buffer_load_dwordx4 v242, s[24:27], s7 offen lds
	s_nop 0
	s_mov_b32 m0, s76
	s_nop 0
	buffer_load_dwordx4 v243, s[24:27], s7 offen lds
	s_waitcnt vmcnt(8)
	s_waitcnt lgkmcnt(0)
	s_barrier
	s_setprio 1
	v_mfma_f32_16x16x32_bf16 v[76:79], v[48:51], v[192:195], v[76:79]
	v_mfma_f32_16x16x32_bf16 v[68:71], v[64:67], v[192:195], v[68:71]
	v_mfma_f32_16x16x32_bf16 v[60:63], v[48:51], v[200:203], v[60:63]
	v_mfma_f32_16x16x32_bf16 v[52:55], v[64:67], v[200:203], v[52:55]
	v_mfma_f32_16x16x32_bf16 v[44:47], v[48:51], v[220:223], v[44:47]
	v_mfma_f32_16x16x32_bf16 v[36:39], v[64:67], v[220:223], v[36:39]
	v_mfma_f32_16x16x32_bf16 v[12:15], v[48:51], v[228:231], v[12:15]
	v_mfma_f32_16x16x32_bf16 v[4:7], v[64:67], v[228:231], v[4:7]
	v_mfma_f32_16x16x32_bf16 v[76:79], v[56:59], v[196:199], v[76:79]
	v_mfma_f32_16x16x32_bf16 v[68:71], v[72:75], v[196:199], v[68:71]
	v_mfma_f32_16x16x32_bf16 v[60:63], v[56:59], v[204:207], v[60:63]
	v_mfma_f32_16x16x32_bf16 v[52:55], v[72:75], v[204:207], v[52:55]
	v_mfma_f32_16x16x32_bf16 v[44:47], v[56:59], v[224:227], v[44:47]
	v_mfma_f32_16x16x32_bf16 v[36:39], v[72:75], v[224:227], v[36:39]
	v_mfma_f32_16x16x32_bf16 v[12:15], v[56:59], v[246:249], v[12:15]
	v_mfma_f32_16x16x32_bf16 v[4:7], v[72:75], v[246:249], v[4:7]
	v_mfma_f32_16x16x32_bf16 v[16:19], v[152:155], v[192:195], v[16:19]
	v_mfma_f32_16x16x32_bf16 v[72:75], v[160:163], v[196:199], v[16:19]
	v_mfma_f32_16x16x32_bf16 v[16:19], v[168:171], v[192:195], v[20:23]
	v_mfma_f32_16x16x32_bf16 v[64:67], v[176:179], v[196:199], v[16:19]
	v_mfma_f32_16x16x32_bf16 v[16:19], v[152:155], v[200:203], v[24:27]
	v_mfma_f32_16x16x32_bf16 v[56:59], v[160:163], v[204:207], v[16:19]
	v_mfma_f32_16x16x32_bf16 v[16:19], v[168:171], v[200:203], v[28:31]
	v_mfma_f32_16x16x32_bf16 v[48:51], v[176:179], v[204:207], v[16:19]
	v_mfma_f32_16x16x32_bf16 v[16:19], v[152:155], v[220:223], v[40:43]
	v_mfma_f32_16x16x32_bf16 v[40:43], v[160:163], v[224:227], v[16:19]
	v_mfma_f32_16x16x32_bf16 v[16:19], v[168:171], v[220:223], v[32:35]
	v_mfma_f32_16x16x32_bf16 v[8:11], v[152:155], v[228:231], v[8:11]
	v_mfma_f32_16x16x32_bf16 v[0:3], v[168:171], v[228:231], v[0:3]
	v_mfma_f32_16x16x32_bf16 v[32:35], v[176:179], v[224:227], v[16:19]
	v_mfma_f32_16x16x32_bf16 v[8:11], v[160:163], v[246:249], v[8:11]
	v_mfma_f32_16x16x32_bf16 v[0:3], v[176:179], v[246:249], v[0:3]
	s_setprio 0
	s_barrier
	s_add_i32 s6, s6, 2
	s_add_i32 s4, s4, 0x8000
	s_add_i32 s5, s5, 0x8000
	s_cmp_gt_u32 s6, 29
	s_cbranch_scc0 .LBB0_143

.LBB0_594:
	v_add_u32_e32 v80, 0x10000, v226
	ds_read_b128 v[152:155], v80
	ds_read_b128 v[156:159], v80 offset:1024
	ds_read_b128 v[160:163], v80 offset:2048
	ds_read_b128 v[164:167], v80 offset:3072
	v_add_u32_e32 v80, 0x14000, v226
	ds_read_b128 v[168:171], v80
	ds_read_b128 v[172:175], v80 offset:1024
	ds_read_b128 v[176:179], v80 offset:2048
	ds_read_b128 v[180:183], v80 offset:3072
	s_add_i32 s97, s96, s39
	s_add_i32 s94, s97, 0x8000
	s_add_i32 s95, s93, s39
	s_cmp_eq_u32 s39, 0x78000
	s_cselect_b32 s36, vcc_lo, s94
	s_cselect_b32 s95, vcc_hi, s95
	s_or_b32 s94, s36, 0x4000
	ds_read_b128 v[184:187], v227
	ds_read_b128 v[188:191], v227 offset:1024
	ds_read_b128 v[192:195], v227 offset:2048
	ds_read_b128 v[196:199], v227 offset:3072
	ds_read_b128 v[200:203], v227 offset:4096
	ds_read_b128 v[204:207], v227 offset:5120
	ds_read_b128 v[228:231], v227 offset:6144
	ds_read_b128 v[240:243], v227 offset:7168
	s_add_i32 s97, s97, 0x84000
	s_mov_b32 m0, s85
	s_nop 0
	buffer_load_dwordx4 v224, s[60:63], s97 offen lds
	s_nop 0
	s_mov_b32 m0, s86
	s_nop 0
	buffer_load_dwordx4 v225, s[60:63], s97 offen lds
	s_waitcnt vmcnt(8)
	s_waitcnt lgkmcnt(0)
	s_barrier
	s_setprio 1
	v_mfma_f32_16x16x32_bf16 v[148:151], v[152:155], v[184:187], v[148:151]
	v_mfma_f32_16x16x32_bf16 v[144:147], v[160:163], v[184:187], v[144:147]
	v_mfma_f32_16x16x32_bf16 v[132:135], v[152:155], v[192:195], v[132:135]
	v_mfma_f32_16x16x32_bf16 v[128:131], v[160:163], v[192:195], v[128:131]
	v_mfma_f32_16x16x32_bf16 v[116:119], v[152:155], v[200:203], v[116:119]
	v_mfma_f32_16x16x32_bf16 v[112:115], v[160:163], v[200:203], v[112:115]
	v_mfma_f32_16x16x32_bf16 v[76:79], v[152:155], v[228:231], v[76:79]
	v_mfma_f32_16x16x32_bf16 v[72:75], v[160:163], v[228:231], v[72:75]
	v_mfma_f32_16x16x32_bf16 v[148:151], v[156:159], v[188:191], v[148:151]
	v_mfma_f32_16x16x32_bf16 v[144:147], v[164:167], v[188:191], v[144:147]
	v_mfma_f32_16x16x32_bf16 v[132:135], v[156:159], v[196:199], v[132:135]
	v_mfma_f32_16x16x32_bf16 v[128:131], v[164:167], v[196:199], v[128:131]
	v_mfma_f32_16x16x32_bf16 v[116:119], v[156:159], v[204:207], v[116:119]
	v_mfma_f32_16x16x32_bf16 v[112:115], v[164:167], v[204:207], v[112:115]
	v_mfma_f32_16x16x32_bf16 v[76:79], v[156:159], v[240:243], v[76:79]
	v_mfma_f32_16x16x32_bf16 v[72:75], v[164:167], v[240:243], v[72:75]
	v_mfma_f32_16x16x32_bf16 v[140:143], v[168:171], v[184:187], v[140:143]
	v_mfma_f32_16x16x32_bf16 v[136:139], v[176:179], v[184:187], v[136:139]
	v_mfma_f32_16x16x32_bf16 v[124:127], v[168:171], v[192:195], v[124:127]
	v_mfma_f32_16x16x32_bf16 v[120:123], v[176:179], v[192:195], v[120:123]
	v_mfma_f32_16x16x32_bf16 v[108:111], v[168:171], v[200:203], v[108:111]
	v_mfma_f32_16x16x32_bf16 v[104:107], v[176:179], v[200:203], v[104:107]
	v_mfma_f32_16x16x32_bf16 v[68:71], v[168:171], v[228:231], v[68:71]
	v_mfma_f32_16x16x32_bf16 v[64:67], v[176:179], v[228:231], v[64:67]
	v_mfma_f32_16x16x32_bf16 v[140:143], v[172:175], v[188:191], v[140:143]
	v_mfma_f32_16x16x32_bf16 v[136:139], v[180:183], v[188:191], v[136:139]
	v_mfma_f32_16x16x32_bf16 v[124:127], v[172:175], v[196:199], v[124:127]
	v_mfma_f32_16x16x32_bf16 v[120:123], v[180:183], v[196:199], v[120:123]
	v_mfma_f32_16x16x32_bf16 v[108:111], v[172:175], v[204:207], v[108:111]
	v_mfma_f32_16x16x32_bf16 v[104:107], v[180:183], v[204:207], v[104:107]
	v_mfma_f32_16x16x32_bf16 v[68:71], v[172:175], v[240:243], v[68:71]
	v_mfma_f32_16x16x32_bf16 v[64:67], v[180:183], v[240:243], v[64:67]
	s_setprio 0
	s_barrier
	ds_read_b128 v[184:187], v227 offset:16384
	ds_read_b128 v[188:191], v227 offset:17408
	ds_read_b128 v[192:195], v227 offset:18432
	ds_read_b128 v[196:199], v227 offset:19456
	ds_read_b128 v[200:203], v227 offset:20480
	ds_read_b128 v[204:207], v227 offset:21504
	ds_read_b128 v[228:231], v227 offset:22528
	ds_read_b128 v[240:243], v227 offset:23552
	s_mov_b32 m0, s34
	s_nop 0
	buffer_load_dwordx4 v224, s[48:51], s95 offen lds
	s_add_i32 s97, s95, 0x80000
	s_mov_b32 m0, s55
	s_nop 0
	buffer_load_dwordx4 v225, s[48:51], s95 offen lds
	s_nop 0
	s_mov_b32 m0, s72
	s_nop 0
	buffer_load_dwordx4 v224, s[48:51], s97 offen lds
	s_nop 0
	s_mov_b32 m0, s73
	s_nop 0
	buffer_load_dwordx4 v225, s[48:51], s97 offen lds
	s_nop 0
	s_mov_b32 m0, s31
	s_nop 0
	buffer_load_dwordx4 v224, s[60:63], s36 offen lds
	s_nop 0
	s_mov_b32 m0, s74
	s_nop 0
	buffer_load_dwordx4 v225, s[60:63], s36 offen lds
	s_waitcnt vmcnt(8)
	s_waitcnt lgkmcnt(0)
	s_barrier
	s_setprio 1
	v_mfma_f32_16x16x32_bf16 v[60:63], v[152:155], v[184:187], v[60:63]
	v_mfma_f32_16x16x32_bf16 v[56:59], v[160:163], v[184:187], v[56:59]
	v_mfma_f32_16x16x32_bf16 v[44:47], v[152:155], v[192:195], v[44:47]
	v_mfma_f32_16x16x32_bf16 v[40:43], v[160:163], v[192:195], v[40:43]
	v_mfma_f32_16x16x32_bf16 v[28:31], v[152:155], v[200:203], v[28:31]
	v_mfma_f32_16x16x32_bf16 v[24:27], v[160:163], v[200:203], v[24:27]
	v_mfma_f32_16x16x32_bf16 v[12:15], v[152:155], v[228:231], v[12:15]
	v_mfma_f32_16x16x32_bf16 v[8:11], v[160:163], v[228:231], v[8:11]
	v_mfma_f32_16x16x32_bf16 v[60:63], v[156:159], v[188:191], v[60:63]
	v_mfma_f32_16x16x32_bf16 v[56:59], v[164:167], v[188:191], v[56:59]
	v_mfma_f32_16x16x32_bf16 v[44:47], v[156:159], v[196:199], v[44:47]
	v_mfma_f32_16x16x32_bf16 v[40:43], v[164:167], v[196:199], v[40:43]
	v_mfma_f32_16x16x32_bf16 v[28:31], v[156:159], v[204:207], v[28:31]
	v_mfma_f32_16x16x32_bf16 v[24:27], v[164:167], v[204:207], v[24:27]
	v_mfma_f32_16x16x32_bf16 v[12:15], v[156:159], v[240:243], v[12:15]
	v_mfma_f32_16x16x32_bf16 v[8:11], v[164:167], v[240:243], v[8:11]
	v_mfma_f32_16x16x32_bf16 v[52:55], v[168:171], v[184:187], v[52:55]
	v_mfma_f32_16x16x32_bf16 v[48:51], v[176:179], v[184:187], v[48:51]
	v_mfma_f32_16x16x32_bf16 v[36:39], v[168:171], v[192:195], v[36:39]
	v_mfma_f32_16x16x32_bf16 v[32:35], v[176:179], v[192:195], v[32:35]
	v_mfma_f32_16x16x32_bf16 v[20:23], v[168:171], v[200:203], v[20:23]
	v_mfma_f32_16x16x32_bf16 v[16:19], v[176:179], v[200:203], v[16:19]
	v_mfma_f32_16x16x32_bf16 v[4:7], v[168:171], v[228:231], v[4:7]
	v_mfma_f32_16x16x32_bf16 v[0:3], v[176:179], v[228:231], v[0:3]
	v_mfma_f32_16x16x32_bf16 v[52:55], v[172:175], v[188:191], v[52:55]
	v_mfma_f32_16x16x32_bf16 v[48:51], v[180:183], v[188:191], v[48:51]
	v_mfma_f32_16x16x32_bf16 v[36:39], v[172:175], v[196:199], v[36:39]
	v_mfma_f32_16x16x32_bf16 v[32:35], v[180:183], v[196:199], v[32:35]
	v_mfma_f32_16x16x32_bf16 v[20:23], v[172:175], v[204:207], v[20:23]
	v_mfma_f32_16x16x32_bf16 v[16:19], v[180:183], v[204:207], v[16:19]
	v_mfma_f32_16x16x32_bf16 v[4:7], v[172:175], v[240:243], v[4:7]
	v_mfma_f32_16x16x32_bf16 v[0:3], v[180:183], v[240:243], v[0:3]
	s_setprio 0
	s_barrier
	v_add_u32_e32 v80, 0x18000, v226
	ds_read_b128 v[152:155], v80
	ds_read_b128 v[156:159], v80 offset:1024
	ds_read_b128 v[160:163], v80 offset:2048
	ds_read_b128 v[164:167], v80 offset:3072
	v_add_u32_e32 v80, 0x1c000, v226
	ds_read_b128 v[168:171], v80
	ds_read_b128 v[172:175], v80 offset:1024
	ds_read_b128 v[176:179], v80 offset:2048
	ds_read_b128 v[180:183], v80 offset:3072
	ds_read_b128 v[184:187], v227 offset:32768
	ds_read_b128 v[188:191], v227 offset:33792
	ds_read_b128 v[192:195], v227 offset:34816
	ds_read_b128 v[196:199], v227 offset:35840
	ds_read_b128 v[200:203], v227 offset:36864
	ds_read_b128 v[204:207], v227 offset:37888
	ds_read_b128 v[228:231], v227 offset:38912
	ds_read_b128 v[240:243], v227 offset:39936
	s_add_i32 s36, s36, 0x80000
	s_mov_b32 m0, s75
	s_nop 0
	buffer_load_dwordx4 v224, s[60:63], s36 offen lds
	s_nop 0
	s_mov_b32 m0, s76
	s_nop 0
	buffer_load_dwordx4 v225, s[60:63], s36 offen lds
	s_waitcnt vmcnt(8)
	s_waitcnt lgkmcnt(0)
	s_barrier
	s_setprio 1
	v_mfma_f32_16x16x32_bf16 v[148:151], v[152:155], v[184:187], v[148:151]
	v_mfma_f32_16x16x32_bf16 v[144:147], v[160:163], v[184:187], v[144:147]
	v_mfma_f32_16x16x32_bf16 v[132:135], v[152:155], v[192:195], v[132:135]
	v_mfma_f32_16x16x32_bf16 v[128:131], v[160:163], v[192:195], v[128:131]
	v_mfma_f32_16x16x32_bf16 v[116:119], v[152:155], v[200:203], v[116:119]
	v_mfma_f32_16x16x32_bf16 v[112:115], v[160:163], v[200:203], v[112:115]
	v_mfma_f32_16x16x32_bf16 v[76:79], v[152:155], v[228:231], v[76:79]
	v_mfma_f32_16x16x32_bf16 v[72:75], v[160:163], v[228:231], v[72:75]
	v_mfma_f32_16x16x32_bf16 v[148:151], v[156:159], v[188:191], v[148:151]
	v_mfma_f32_16x16x32_bf16 v[144:147], v[164:167], v[188:191], v[144:147]
	v_mfma_f32_16x16x32_bf16 v[132:135], v[156:159], v[196:199], v[132:135]
	v_mfma_f32_16x16x32_bf16 v[128:131], v[164:167], v[196:199], v[128:131]
	v_mfma_f32_16x16x32_bf16 v[116:119], v[156:159], v[204:207], v[116:119]
	v_mfma_f32_16x16x32_bf16 v[112:115], v[164:167], v[204:207], v[112:115]
	v_mfma_f32_16x16x32_bf16 v[76:79], v[156:159], v[240:243], v[76:79]
	v_mfma_f32_16x16x32_bf16 v[72:75], v[164:167], v[240:243], v[72:75]
	v_mfma_f32_16x16x32_bf16 v[140:143], v[168:171], v[184:187], v[140:143]
	v_mfma_f32_16x16x32_bf16 v[136:139], v[176:179], v[184:187], v[136:139]
	v_mfma_f32_16x16x32_bf16 v[124:127], v[168:171], v[192:195], v[124:127]
	v_mfma_f32_16x16x32_bf16 v[120:123], v[176:179], v[192:195], v[120:123]
	v_mfma_f32_16x16x32_bf16 v[108:111], v[168:171], v[200:203], v[108:111]
	v_mfma_f32_16x16x32_bf16 v[104:107], v[176:179], v[200:203], v[104:107]
	v_mfma_f32_16x16x32_bf16 v[68:71], v[168:171], v[228:231], v[68:71]
	v_mfma_f32_16x16x32_bf16 v[64:67], v[176:179], v[228:231], v[64:67]
	v_mfma_f32_16x16x32_bf16 v[140:143], v[172:175], v[188:191], v[140:143]
	v_mfma_f32_16x16x32_bf16 v[136:139], v[180:183], v[188:191], v[136:139]
	v_mfma_f32_16x16x32_bf16 v[124:127], v[172:175], v[196:199], v[124:127]
	v_mfma_f32_16x16x32_bf16 v[120:123], v[180:183], v[196:199], v[120:123]
	v_mfma_f32_16x16x32_bf16 v[108:111], v[172:175], v[204:207], v[108:111]
	v_mfma_f32_16x16x32_bf16 v[104:107], v[180:183], v[204:207], v[104:107]
	v_mfma_f32_16x16x32_bf16 v[68:71], v[172:175], v[240:243], v[68:71]
	v_mfma_f32_16x16x32_bf16 v[64:67], v[180:183], v[240:243], v[64:67]
	s_setprio 0
	s_barrier
	ds_read_b128 v[184:187], v227 offset:49152
	ds_read_b128 v[188:191], v227 offset:50176
	ds_read_b128 v[192:195], v227 offset:51200
	ds_read_b128 v[196:199], v227 offset:52224
	ds_read_b128 v[200:203], v227 offset:53248
	ds_read_b128 v[204:207], v227 offset:54272
	ds_read_b128 v[228:231], v227 offset:55296
	ds_read_b128 v[240:243], v227 offset:56320
	s_or_b32 s36, s95, 0x4000
	s_mov_b32 m0, s77
	s_nop 0
	buffer_load_dwordx4 v224, s[48:51], s36 offen lds
	s_nop 0
	s_mov_b32 m0, s78
	s_nop 0
	buffer_load_dwordx4 v225, s[48:51], s36 offen lds
	s_add_i32 s36, s95, 0x84000
	s_mov_b32 m0, s83
	s_nop 0
	buffer_load_dwordx4 v224, s[48:51], s36 offen lds
	s_nop 0
	s_mov_b32 m0, s84
	s_nop 0
	buffer_load_dwordx4 v225, s[48:51], s36 offen lds
	s_nop 0
	s_mov_b32 m0, s79
	s_nop 0
	buffer_load_dwordx4 v224, s[60:63], s94 offen lds
	s_nop 0
	s_mov_b32 m0, s82
	s_nop 0
	buffer_load_dwordx4 v225, s[60:63], s94 offen lds
	s_waitcnt vmcnt(8)
	s_waitcnt lgkmcnt(0)
	s_barrier
	s_setprio 1
	v_mfma_f32_16x16x32_bf16 v[60:63], v[152:155], v[184:187], v[60:63]
	v_mfma_f32_16x16x32_bf16 v[56:59], v[160:163], v[184:187], v[56:59]
	v_mfma_f32_16x16x32_bf16 v[44:47], v[152:155], v[192:195], v[44:47]
	v_mfma_f32_16x16x32_bf16 v[40:43], v[160:163], v[192:195], v[40:43]
	v_mfma_f32_16x16x32_bf16 v[28:31], v[152:155], v[200:203], v[28:31]
	v_mfma_f32_16x16x32_bf16 v[24:27], v[160:163], v[200:203], v[24:27]
	v_mfma_f32_16x16x32_bf16 v[12:15], v[152:155], v[228:231], v[12:15]
	v_mfma_f32_16x16x32_bf16 v[8:11], v[160:163], v[228:231], v[8:11]
	v_mfma_f32_16x16x32_bf16 v[60:63], v[156:159], v[188:191], v[60:63]
	v_mfma_f32_16x16x32_bf16 v[56:59], v[164:167], v[188:191], v[56:59]
	v_mfma_f32_16x16x32_bf16 v[44:47], v[156:159], v[196:199], v[44:47]
	v_mfma_f32_16x16x32_bf16 v[40:43], v[164:167], v[196:199], v[40:43]
	v_mfma_f32_16x16x32_bf16 v[28:31], v[156:159], v[204:207], v[28:31]
	v_mfma_f32_16x16x32_bf16 v[24:27], v[164:167], v[204:207], v[24:27]
	v_mfma_f32_16x16x32_bf16 v[12:15], v[156:159], v[240:243], v[12:15]
	v_mfma_f32_16x16x32_bf16 v[8:11], v[164:167], v[240:243], v[8:11]
	v_mfma_f32_16x16x32_bf16 v[52:55], v[168:171], v[184:187], v[52:55]
	v_mfma_f32_16x16x32_bf16 v[48:51], v[176:179], v[184:187], v[48:51]
	v_mfma_f32_16x16x32_bf16 v[36:39], v[168:171], v[192:195], v[36:39]
	v_mfma_f32_16x16x32_bf16 v[32:35], v[176:179], v[192:195], v[32:35]
	v_mfma_f32_16x16x32_bf16 v[20:23], v[168:171], v[200:203], v[20:23]
	v_mfma_f32_16x16x32_bf16 v[16:19], v[176:179], v[200:203], v[16:19]
	v_mfma_f32_16x16x32_bf16 v[4:7], v[168:171], v[228:231], v[4:7]
	v_mfma_f32_16x16x32_bf16 v[0:3], v[176:179], v[228:231], v[0:3]
	v_mfma_f32_16x16x32_bf16 v[52:55], v[172:175], v[188:191], v[52:55]
	v_mfma_f32_16x16x32_bf16 v[48:51], v[180:183], v[188:191], v[48:51]
	v_mfma_f32_16x16x32_bf16 v[36:39], v[172:175], v[196:199], v[36:39]
	v_mfma_f32_16x16x32_bf16 v[32:35], v[180:183], v[196:199], v[32:35]
	v_mfma_f32_16x16x32_bf16 v[20:23], v[172:175], v[204:207], v[20:23]
	v_mfma_f32_16x16x32_bf16 v[16:19], v[180:183], v[204:207], v[16:19]
	v_mfma_f32_16x16x32_bf16 v[4:7], v[172:175], v[240:243], v[4:7]
	v_mfma_f32_16x16x32_bf16 v[0:3], v[180:183], v[240:243], v[0:3]
	s_setprio 0
	s_barrier
	s_add_i32 s38, s38, 2
	s_add_i32 s39, s39, 0x8000
	s_cmp_gt_u32 s38, 29
	s_cbranch_scc1 .LBB0_597

.Lnb_p4:
	s_add_i32 s11, s8, 0xfff84000
	s_cmp_eq_u32 s10, 28
	s_cselect_b32 s13, s6, s11
	s_cselect_b32 s12, s7, s9
	s_or_b32 s11, s13, 0x4000
	s_mov_b32 m0, s89
	s_nop 0
	buffer_load_dwordx4 v220, s[64:67], s8 offen lds
	s_nop 0
	s_mov_b32 m0, s91
	s_nop 0
	buffer_load_dwordx4 v221, s[64:67], s8 offen lds
	s_waitcnt vmcnt(24)
	s_waitcnt lgkmcnt(0)
	s_barrier
	s_setprio 1
	v_mfma_f32_16x16x32_bf16 v[164:167], v[128:131], v[184:187], 0
	v_mfma_f32_16x16x32_bf16 v[160:163], v[152:155], v[184:187], 0
	v_mfma_f32_16x16x32_bf16 v[136:139], v[128:131], v[192:195], 0
	v_mfma_f32_16x16x32_bf16 v[132:135], v[152:155], v[192:195], 0
	v_mfma_f32_16x16x32_bf16 v[116:119], v[128:131], v[200:203], 0
	v_mfma_f32_16x16x32_bf16 v[112:115], v[152:155], v[200:203], 0
	v_mfma_f32_16x16x32_bf16 v[76:79], v[128:131], v[224:227], 0
	v_mfma_f32_16x16x32_bf16 v[72:75], v[152:155], v[224:227], 0
	v_mfma_f32_16x16x32_bf16 v[164:167], v[140:143], v[188:191], v[164:167]
	v_mfma_f32_16x16x32_bf16 v[160:163], v[156:159], v[188:191], v[160:163]
	v_mfma_f32_16x16x32_bf16 v[136:139], v[140:143], v[196:199], v[136:139]
	v_mfma_f32_16x16x32_bf16 v[132:135], v[156:159], v[196:199], v[132:135]
	v_mfma_f32_16x16x32_bf16 v[116:119], v[140:143], v[204:207], v[116:119]
	v_mfma_f32_16x16x32_bf16 v[112:115], v[156:159], v[204:207], v[112:115]
	v_mfma_f32_16x16x32_bf16 v[76:79], v[140:143], v[228:231], v[76:79]
	v_mfma_f32_16x16x32_bf16 v[72:75], v[156:159], v[228:231], v[72:75]
	v_mfma_f32_16x16x32_bf16 v[148:151], v[168:171], v[184:187], 0
	v_mfma_f32_16x16x32_bf16 v[144:147], v[176:179], v[184:187], 0
	v_mfma_f32_16x16x32_bf16 v[124:127], v[168:171], v[192:195], 0
	v_mfma_f32_16x16x32_bf16 v[120:123], v[176:179], v[192:195], 0
	v_mfma_f32_16x16x32_bf16 v[108:111], v[168:171], v[200:203], 0
	v_mfma_f32_16x16x32_bf16 v[104:107], v[176:179], v[200:203], 0
	v_mfma_f32_16x16x32_bf16 v[68:71], v[168:171], v[224:227], 0
	v_mfma_f32_16x16x32_bf16 v[64:67], v[176:179], v[224:227], 0
	v_mfma_f32_16x16x32_bf16 v[148:151], v[172:175], v[188:191], v[148:151]
	v_mfma_f32_16x16x32_bf16 v[144:147], v[180:183], v[188:191], v[144:147]
	v_mfma_f32_16x16x32_bf16 v[124:127], v[172:175], v[196:199], v[124:127]
	v_mfma_f32_16x16x32_bf16 v[120:123], v[180:183], v[196:199], v[120:123]
	v_mfma_f32_16x16x32_bf16 v[108:111], v[172:175], v[204:207], v[108:111]
	v_mfma_f32_16x16x32_bf16 v[104:107], v[180:183], v[204:207], v[104:107]
	v_mfma_f32_16x16x32_bf16 v[68:71], v[172:175], v[228:231], v[68:71]
	v_mfma_f32_16x16x32_bf16 v[64:67], v[180:183], v[228:231], v[64:67]
	s_setprio 0
	s_barrier
	ds_read_b128 v[184:187], v223 offset:16384
	ds_read_b128 v[188:191], v223 offset:17408
	ds_read_b128 v[192:195], v223 offset:18432
	ds_read_b128 v[196:199], v223 offset:19456
	ds_read_b128 v[200:203], v223 offset:20480
	ds_read_b128 v[204:207], v223 offset:21504
	ds_read_b128 v[224:227], v223 offset:22528
	ds_read_b128 v[228:231], v223 offset:23552
	s_mov_b32 m0, s55
	s_nop 0
	buffer_load_dwordx4 v220, s[48:51], s12 offen lds
	s_add_i32 s14, s12, 0x80000
	s_mov_b32 m0, s76
	s_nop 0
	buffer_load_dwordx4 v221, s[48:51], s12 offen lds
	s_nop 0
	s_mov_b32 m0, s77
	s_nop 0
	buffer_load_dwordx4 v220, s[48:51], s14 offen lds
	s_nop 0
	s_mov_b32 m0, s78
	s_nop 0
	buffer_load_dwordx4 v221, s[48:51], s14 offen lds
	s_nop 0
	s_mov_b32 m0, s31
	s_nop 0
	buffer_load_dwordx4 v220, s[64:67], s13 offen lds
	s_nop 0
	s_mov_b32 m0, s79
	s_nop 0
	buffer_load_dwordx4 v221, s[64:67], s13 offen lds
	s_waitcnt vmcnt(24)
	s_waitcnt lgkmcnt(0)
	s_barrier
	s_setprio 1
	v_mfma_f32_16x16x32_bf16 v[60:63], v[128:131], v[184:187], 0
	v_mfma_f32_16x16x32_bf16 v[56:59], v[152:155], v[184:187], 0
	v_mfma_f32_16x16x32_bf16 v[44:47], v[128:131], v[192:195], 0
	v_mfma_f32_16x16x32_bf16 v[40:43], v[152:155], v[192:195], 0
	v_mfma_f32_16x16x32_bf16 v[28:31], v[128:131], v[200:203], 0
	v_mfma_f32_16x16x32_bf16 v[24:27], v[152:155], v[200:203], 0
	v_mfma_f32_16x16x32_bf16 v[12:15], v[128:131], v[224:227], 0
	v_mfma_f32_16x16x32_bf16 v[8:11], v[152:155], v[224:227], 0
	v_mfma_f32_16x16x32_bf16 v[60:63], v[140:143], v[188:191], v[60:63]
	v_mfma_f32_16x16x32_bf16 v[56:59], v[156:159], v[188:191], v[56:59]
	v_mfma_f32_16x16x32_bf16 v[44:47], v[140:143], v[196:199], v[44:47]
	v_mfma_f32_16x16x32_bf16 v[40:43], v[156:159], v[196:199], v[40:43]
	v_mfma_f32_16x16x32_bf16 v[28:31], v[140:143], v[204:207], v[28:31]
	v_mfma_f32_16x16x32_bf16 v[24:27], v[156:159], v[204:207], v[24:27]
	v_mfma_f32_16x16x32_bf16 v[12:15], v[140:143], v[228:231], v[12:15]
	v_mfma_f32_16x16x32_bf16 v[8:11], v[156:159], v[228:231], v[8:11]
	v_mfma_f32_16x16x32_bf16 v[52:55], v[168:171], v[184:187], 0
	v_mfma_f32_16x16x32_bf16 v[48:51], v[176:179], v[184:187], 0
	v_mfma_f32_16x16x32_bf16 v[36:39], v[168:171], v[192:195], 0
	v_mfma_f32_16x16x32_bf16 v[32:35], v[176:179], v[192:195], 0
	v_mfma_f32_16x16x32_bf16 v[20:23], v[168:171], v[200:203], 0
	v_mfma_f32_16x16x32_bf16 v[16:19], v[176:179], v[200:203], 0
	v_mfma_f32_16x16x32_bf16 v[4:7], v[168:171], v[224:227], 0
	v_mfma_f32_16x16x32_bf16 v[0:3], v[176:179], v[224:227], 0
	v_mfma_f32_16x16x32_bf16 v[52:55], v[172:175], v[188:191], v[52:55]
	v_mfma_f32_16x16x32_bf16 v[48:51], v[180:183], v[188:191], v[48:51]
	v_mfma_f32_16x16x32_bf16 v[36:39], v[172:175], v[196:199], v[36:39]
	v_mfma_f32_16x16x32_bf16 v[32:35], v[180:183], v[196:199], v[32:35]
	v_mfma_f32_16x16x32_bf16 v[20:23], v[172:175], v[204:207], v[20:23]
	v_mfma_f32_16x16x32_bf16 v[16:19], v[180:183], v[204:207], v[16:19]
	v_mfma_f32_16x16x32_bf16 v[4:7], v[172:175], v[228:231], v[4:7]
	v_mfma_f32_16x16x32_bf16 v[0:3], v[180:183], v[228:231], v[0:3]
	s_setprio 0
	s_barrier
	v_add_u32_e32 v156, 0x18000, v222
	v_add_u32_e32 v180, 0x1c000, v222
	ds_read_b128 v[128:131], v156
	ds_read_b128 v[140:143], v156 offset:1024
	ds_read_b128 v[152:155], v156 offset:2048
	ds_read_b128 v[156:159], v156 offset:3072
	ds_read_b128 v[168:171], v180
	ds_read_b128 v[172:175], v180 offset:1024
	ds_read_b128 v[176:179], v180 offset:2048
	ds_read_b128 v[180:183], v180 offset:3072
	ds_read_b128 v[184:187], v223 offset:32768
	ds_read_b128 v[188:191], v223 offset:33792
	ds_read_b128 v[192:195], v223 offset:34816
	ds_read_b128 v[196:199], v223 offset:35840
	ds_read_b128 v[200:203], v223 offset:36864
	ds_read_b128 v[204:207], v223 offset:37888
	ds_read_b128 v[224:227], v223 offset:38912
	ds_read_b128 v[228:231], v223 offset:39936
	s_add_i32 s13, s13, 0x80000
	s_mov_b32 m0, s82
	s_nop 0
	buffer_load_dwordx4 v220, s[64:67], s13 offen lds
	s_nop 0
	s_mov_b32 m0, s83
	s_nop 0
	buffer_load_dwordx4 v221, s[64:67], s13 offen lds
	s_waitcnt vmcnt(8)
	s_waitcnt lgkmcnt(0)
	s_barrier
	s_setprio 1
	v_mfma_f32_16x16x32_bf16 v[164:167], v[128:131], v[184:187], v[164:167]
	v_mfma_f32_16x16x32_bf16 v[160:163], v[152:155], v[184:187], v[160:163]
	v_mfma_f32_16x16x32_bf16 v[136:139], v[128:131], v[192:195], v[136:139]
	v_mfma_f32_16x16x32_bf16 v[132:135], v[152:155], v[192:195], v[132:135]
	v_mfma_f32_16x16x32_bf16 v[116:119], v[128:131], v[200:203], v[116:119]
	v_mfma_f32_16x16x32_bf16 v[112:115], v[152:155], v[200:203], v[112:115]
	v_mfma_f32_16x16x32_bf16 v[76:79], v[128:131], v[224:227], v[76:79]
	v_mfma_f32_16x16x32_bf16 v[72:75], v[152:155], v[224:227], v[72:75]
	v_mfma_f32_16x16x32_bf16 v[164:167], v[140:143], v[188:191], v[164:167]
	v_mfma_f32_16x16x32_bf16 v[160:163], v[156:159], v[188:191], v[160:163]
	v_mfma_f32_16x16x32_bf16 v[136:139], v[140:143], v[196:199], v[136:139]
	v_mfma_f32_16x16x32_bf16 v[132:135], v[156:159], v[196:199], v[132:135]
	v_mfma_f32_16x16x32_bf16 v[116:119], v[140:143], v[204:207], v[116:119]
	v_mfma_f32_16x16x32_bf16 v[112:115], v[156:159], v[204:207], v[112:115]
	v_mfma_f32_16x16x32_bf16 v[76:79], v[140:143], v[228:231], v[76:79]
	v_mfma_f32_16x16x32_bf16 v[72:75], v[156:159], v[228:231], v[72:75]
	v_mfma_f32_16x16x32_bf16 v[148:151], v[168:171], v[184:187], v[148:151]
	v_mfma_f32_16x16x32_bf16 v[144:147], v[176:179], v[184:187], v[144:147]
	v_mfma_f32_16x16x32_bf16 v[124:127], v[168:171], v[192:195], v[124:127]
	v_mfma_f32_16x16x32_bf16 v[120:123], v[176:179], v[192:195], v[120:123]
	v_mfma_f32_16x16x32_bf16 v[108:111], v[168:171], v[200:203], v[108:111]
	v_mfma_f32_16x16x32_bf16 v[104:107], v[176:179], v[200:203], v[104:107]
	v_mfma_f32_16x16x32_bf16 v[68:71], v[168:171], v[224:227], v[68:71]
	v_mfma_f32_16x16x32_bf16 v[64:67], v[176:179], v[224:227], v[64:67]
	v_mfma_f32_16x16x32_bf16 v[148:151], v[172:175], v[188:191], v[148:151]
	v_mfma_f32_16x16x32_bf16 v[144:147], v[180:183], v[188:191], v[144:147]
	v_mfma_f32_16x16x32_bf16 v[124:127], v[172:175], v[196:199], v[124:127]
	v_mfma_f32_16x16x32_bf16 v[120:123], v[180:183], v[196:199], v[120:123]
	v_mfma_f32_16x16x32_bf16 v[108:111], v[172:175], v[204:207], v[108:111]
	v_mfma_f32_16x16x32_bf16 v[104:107], v[180:183], v[204:207], v[104:107]
	v_mfma_f32_16x16x32_bf16 v[68:71], v[172:175], v[228:231], v[68:71]
	v_mfma_f32_16x16x32_bf16 v[64:67], v[180:183], v[228:231], v[64:67]
	s_setprio 0
	s_barrier
	ds_read_b128 v[184:187], v223 offset:49152
	ds_read_b128 v[188:191], v223 offset:50176
	ds_read_b128 v[192:195], v223 offset:51200
	ds_read_b128 v[196:199], v223 offset:52224
	ds_read_b128 v[200:203], v223 offset:53248
	ds_read_b128 v[204:207], v223 offset:54272
	ds_read_b128 v[224:227], v223 offset:55296
	ds_read_b128 v[228:231], v223 offset:56320
	s_or_b32 s13, s12, 0x4000
	s_mov_b32 m0, s34
	s_nop 0
	buffer_load_dwordx4 v220, s[48:51], s13 offen lds
	s_add_i32 s12, s12, 0x84000
	s_mov_b32 m0, s84
	s_nop 0
	buffer_load_dwordx4 v221, s[48:51], s13 offen lds
	s_nop 0
	s_mov_b32 m0, s87
	s_nop 0
	buffer_load_dwordx4 v220, s[48:51], s12 offen lds
	s_nop 0
	s_mov_b32 m0, s88
	s_nop 0
	buffer_load_dwordx4 v221, s[48:51], s12 offen lds
	s_nop 0
	s_mov_b32 m0, s85
	s_nop 0
	buffer_load_dwordx4 v220, s[64:67], s11 offen lds
	s_nop 0
	s_mov_b32 m0, s86
	s_nop 0
	buffer_load_dwordx4 v221, s[64:67], s11 offen lds
	s_waitcnt vmcnt(8)
	s_waitcnt lgkmcnt(0)
	s_barrier
	s_setprio 1
	v_mfma_f32_16x16x32_bf16 v[60:63], v[128:131], v[184:187], v[60:63]
	v_mfma_f32_16x16x32_bf16 v[56:59], v[152:155], v[184:187], v[56:59]
	v_mfma_f32_16x16x32_bf16 v[44:47], v[128:131], v[192:195], v[44:47]
	v_mfma_f32_16x16x32_bf16 v[40:43], v[152:155], v[192:195], v[40:43]
	v_mfma_f32_16x16x32_bf16 v[28:31], v[128:131], v[200:203], v[28:31]
	v_mfma_f32_16x16x32_bf16 v[24:27], v[152:155], v[200:203], v[24:27]
	v_mfma_f32_16x16x32_bf16 v[12:15], v[128:131], v[224:227], v[12:15]
	v_mfma_f32_16x16x32_bf16 v[8:11], v[152:155], v[224:227], v[8:11]
	v_mfma_f32_16x16x32_bf16 v[60:63], v[140:143], v[188:191], v[60:63]
	v_mfma_f32_16x16x32_bf16 v[56:59], v[156:159], v[188:191], v[56:59]
	v_mfma_f32_16x16x32_bf16 v[44:47], v[140:143], v[196:199], v[44:47]
	v_mfma_f32_16x16x32_bf16 v[40:43], v[156:159], v[196:199], v[40:43]
	v_mfma_f32_16x16x32_bf16 v[28:31], v[140:143], v[204:207], v[28:31]
	v_mfma_f32_16x16x32_bf16 v[24:27], v[156:159], v[204:207], v[24:27]
	v_mfma_f32_16x16x32_bf16 v[12:15], v[140:143], v[228:231], v[12:15]
	v_mfma_f32_16x16x32_bf16 v[8:11], v[156:159], v[228:231], v[8:11]
	v_mfma_f32_16x16x32_bf16 v[52:55], v[168:171], v[184:187], v[52:55]
	v_mfma_f32_16x16x32_bf16 v[48:51], v[176:179], v[184:187], v[48:51]
	v_mfma_f32_16x16x32_bf16 v[36:39], v[168:171], v[192:195], v[36:39]
	v_mfma_f32_16x16x32_bf16 v[32:35], v[176:179], v[192:195], v[32:35]
	v_mfma_f32_16x16x32_bf16 v[20:23], v[168:171], v[200:203], v[20:23]
	v_mfma_f32_16x16x32_bf16 v[16:19], v[176:179], v[200:203], v[16:19]
	v_mfma_f32_16x16x32_bf16 v[4:7], v[168:171], v[224:227], v[4:7]
	v_mfma_f32_16x16x32_bf16 v[0:3], v[176:179], v[224:227], v[0:3]
	v_mfma_f32_16x16x32_bf16 v[52:55], v[172:175], v[188:191], v[52:55]
	v_mfma_f32_16x16x32_bf16 v[48:51], v[180:183], v[188:191], v[48:51]
	v_mfma_f32_16x16x32_bf16 v[36:39], v[172:175], v[196:199], v[36:39]
	v_mfma_f32_16x16x32_bf16 v[32:35], v[180:183], v[196:199], v[32:35]
	v_mfma_f32_16x16x32_bf16 v[20:23], v[172:175], v[204:207], v[20:23]
	v_mfma_f32_16x16x32_bf16 v[16:19], v[180:183], v[204:207], v[16:19]
	v_mfma_f32_16x16x32_bf16 v[4:7], v[172:175], v[228:231], v[4:7]
	v_mfma_f32_16x16x32_bf16 v[0:3], v[180:183], v[228:231], v[0:3]
	s_setprio 0
	s_barrier
	s_add_i32 s10, s10, 2
	s_add_i32 s8, s8, 0x8000
	s_add_i32 s9, s9, 0x8000
.LBB0_691:
	v_add_u32_e32 v156, 0x10000, v222
	v_add_u32_e32 v180, 0x14000, v222
	ds_read_b128 v[128:131], v156
	ds_read_b128 v[140:143], v156 offset:1024
	ds_read_b128 v[152:155], v156 offset:2048
	ds_read_b128 v[156:159], v156 offset:3072
	ds_read_b128 v[168:171], v180
	ds_read_b128 v[172:175], v180 offset:1024
	ds_read_b128 v[176:179], v180 offset:2048
	ds_read_b128 v[180:183], v180 offset:3072
	s_add_i32 s11, s8, 0xfff84000
	s_cmp_eq_u32 s10, 28
	s_cselect_b32 s13, s6, s11
	s_cselect_b32 s12, s7, s9
	s_or_b32 s11, s13, 0x4000
	ds_read_b128 v[184:187], v223
	ds_read_b128 v[188:191], v223 offset:1024
	ds_read_b128 v[192:195], v223 offset:2048
	ds_read_b128 v[196:199], v223 offset:3072
	ds_read_b128 v[200:203], v223 offset:4096
	ds_read_b128 v[204:207], v223 offset:5120
	ds_read_b128 v[224:227], v223 offset:6144
	ds_read_b128 v[228:231], v223 offset:7168
	s_mov_b32 m0, s89
	s_nop 0
	buffer_load_dwordx4 v220, s[64:67], s8 offen lds
	s_nop 0
	s_mov_b32 m0, s91
	s_nop 0
	buffer_load_dwordx4 v221, s[64:67], s8 offen lds
	s_waitcnt vmcnt(8)
	s_waitcnt lgkmcnt(0)
	s_barrier
	s_setprio 1
	v_mfma_f32_16x16x32_bf16 v[164:167], v[128:131], v[184:187], v[164:167]
	v_mfma_f32_16x16x32_bf16 v[160:163], v[152:155], v[184:187], v[160:163]
	v_mfma_f32_16x16x32_bf16 v[136:139], v[128:131], v[192:195], v[136:139]
	v_mfma_f32_16x16x32_bf16 v[132:135], v[152:155], v[192:195], v[132:135]
	v_mfma_f32_16x16x32_bf16 v[116:119], v[128:131], v[200:203], v[116:119]
	v_mfma_f32_16x16x32_bf16 v[112:115], v[152:155], v[200:203], v[112:115]
	v_mfma_f32_16x16x32_bf16 v[76:79], v[128:131], v[224:227], v[76:79]
	v_mfma_f32_16x16x32_bf16 v[72:75], v[152:155], v[224:227], v[72:75]
	v_mfma_f32_16x16x32_bf16 v[164:167], v[140:143], v[188:191], v[164:167]
	v_mfma_f32_16x16x32_bf16 v[160:163], v[156:159], v[188:191], v[160:163]
	v_mfma_f32_16x16x32_bf16 v[136:139], v[140:143], v[196:199], v[136:139]
	v_mfma_f32_16x16x32_bf16 v[132:135], v[156:159], v[196:199], v[132:135]
	v_mfma_f32_16x16x32_bf16 v[116:119], v[140:143], v[204:207], v[116:119]
	v_mfma_f32_16x16x32_bf16 v[112:115], v[156:159], v[204:207], v[112:115]
	v_mfma_f32_16x16x32_bf16 v[76:79], v[140:143], v[228:231], v[76:79]
	v_mfma_f32_16x16x32_bf16 v[72:75], v[156:159], v[228:231], v[72:75]
	v_mfma_f32_16x16x32_bf16 v[148:151], v[168:171], v[184:187], v[148:151]
	v_mfma_f32_16x16x32_bf16 v[144:147], v[176:179], v[184:187], v[144:147]
	v_mfma_f32_16x16x32_bf16 v[124:127], v[168:171], v[192:195], v[124:127]
	v_mfma_f32_16x16x32_bf16 v[120:123], v[176:179], v[192:195], v[120:123]
	v_mfma_f32_16x16x32_bf16 v[108:111], v[168:171], v[200:203], v[108:111]
	v_mfma_f32_16x16x32_bf16 v[104:107], v[176:179], v[200:203], v[104:107]
	v_mfma_f32_16x16x32_bf16 v[68:71], v[168:171], v[224:227], v[68:71]
	v_mfma_f32_16x16x32_bf16 v[64:67], v[176:179], v[224:227], v[64:67]
	v_mfma_f32_16x16x32_bf16 v[148:151], v[172:175], v[188:191], v[148:151]
	v_mfma_f32_16x16x32_bf16 v[144:147], v[180:183], v[188:191], v[144:147]
	v_mfma_f32_16x16x32_bf16 v[124:127], v[172:175], v[196:199], v[124:127]
	v_mfma_f32_16x16x32_bf16 v[120:123], v[180:183], v[196:199], v[120:123]
	v_mfma_f32_16x16x32_bf16 v[108:111], v[172:175], v[204:207], v[108:111]
	v_mfma_f32_16x16x32_bf16 v[104:107], v[180:183], v[204:207], v[104:107]
	v_mfma_f32_16x16x32_bf16 v[68:71], v[172:175], v[228:231], v[68:71]
	v_mfma_f32_16x16x32_bf16 v[64:67], v[180:183], v[228:231], v[64:67]
	s_setprio 0
	s_barrier
	ds_read_b128 v[184:187], v223 offset:16384
	ds_read_b128 v[188:191], v223 offset:17408
	ds_read_b128 v[192:195], v223 offset:18432
	ds_read_b128 v[196:199], v223 offset:19456
	ds_read_b128 v[200:203], v223 offset:20480
	ds_read_b128 v[204:207], v223 offset:21504
	ds_read_b128 v[224:227], v223 offset:22528
	ds_read_b128 v[228:231], v223 offset:23552
	s_mov_b32 m0, s55
	s_nop 0
	buffer_load_dwordx4 v220, s[48:51], s12 offen lds
	s_add_i32 s14, s12, 0x80000
	s_mov_b32 m0, s76
	s_nop 0
	buffer_load_dwordx4 v221, s[48:51], s12 offen lds
	s_nop 0
	s_mov_b32 m0, s77
	s_nop 0
	buffer_load_dwordx4 v220, s[48:51], s14 offen lds
	s_nop 0
	s_mov_b32 m0, s78
	s_nop 0
	buffer_load_dwordx4 v221, s[48:51], s14 offen lds
	s_nop 0
	s_mov_b32 m0, s31
	s_nop 0
	buffer_load_dwordx4 v220, s[64:67], s13 offen lds
	s_nop 0
	s_mov_b32 m0, s79
	s_nop 0
	buffer_load_dwordx4 v221, s[64:67], s13 offen lds
	s_waitcnt vmcnt(8)
	s_waitcnt lgkmcnt(0)
	s_barrier
	s_setprio 1
	v_mfma_f32_16x16x32_bf16 v[60:63], v[128:131], v[184:187], v[60:63]
	v_mfma_f32_16x16x32_bf16 v[56:59], v[152:155], v[184:187], v[56:59]
	v_mfma_f32_16x16x32_bf16 v[44:47], v[128:131], v[192:195], v[44:47]
	v_mfma_f32_16x16x32_bf16 v[40:43], v[152:155], v[192:195], v[40:43]
	v_mfma_f32_16x16x32_bf16 v[28:31], v[128:131], v[200:203], v[28:31]
	v_mfma_f32_16x16x32_bf16 v[24:27], v[152:155], v[200:203], v[24:27]
	v_mfma_f32_16x16x32_bf16 v[12:15], v[128:131], v[224:227], v[12:15]
	v_mfma_f32_16x16x32_bf16 v[8:11], v[152:155], v[224:227], v[8:11]
	v_mfma_f32_16x16x32_bf16 v[60:63], v[140:143], v[188:191], v[60:63]
	v_mfma_f32_16x16x32_bf16 v[56:59], v[156:159], v[188:191], v[56:59]
	v_mfma_f32_16x16x32_bf16 v[44:47], v[140:143], v[196:199], v[44:47]
	v_mfma_f32_16x16x32_bf16 v[40:43], v[156:159], v[196:199], v[40:43]
	v_mfma_f32_16x16x32_bf16 v[28:31], v[140:143], v[204:207], v[28:31]
	v_mfma_f32_16x16x32_bf16 v[24:27], v[156:159], v[204:207], v[24:27]
	v_mfma_f32_16x16x32_bf16 v[12:15], v[140:143], v[228:231], v[12:15]
	v_mfma_f32_16x16x32_bf16 v[8:11], v[156:159], v[228:231], v[8:11]
	v_mfma_f32_16x16x32_bf16 v[52:55], v[168:171], v[184:187], v[52:55]
	v_mfma_f32_16x16x32_bf16 v[48:51], v[176:179], v[184:187], v[48:51]
	v_mfma_f32_16x16x32_bf16 v[36:39], v[168:171], v[192:195], v[36:39]
	v_mfma_f32_16x16x32_bf16 v[32:35], v[176:179], v[192:195], v[32:35]
	v_mfma_f32_16x16x32_bf16 v[20:23], v[168:171], v[200:203], v[20:23]
	v_mfma_f32_16x16x32_bf16 v[16:19], v[176:179], v[200:203], v[16:19]
	v_mfma_f32_16x16x32_bf16 v[4:7], v[168:171], v[224:227], v[4:7]
	v_mfma_f32_16x16x32_bf16 v[0:3], v[176:179], v[224:227], v[0:3]
	v_mfma_f32_16x16x32_bf16 v[52:55], v[172:175], v[188:191], v[52:55]
	v_mfma_f32_16x16x32_bf16 v[48:51], v[180:183], v[188:191], v[48:51]
	v_mfma_f32_16x16x32_bf16 v[36:39], v[172:175], v[196:199], v[36:39]
	v_mfma_f32_16x16x32_bf16 v[32:35], v[180:183], v[196:199], v[32:35]
	v_mfma_f32_16x16x32_bf16 v[20:23], v[172:175], v[204:207], v[20:23]
	v_mfma_f32_16x16x32_bf16 v[16:19], v[180:183], v[204:207], v[16:19]
	v_mfma_f32_16x16x32_bf16 v[4:7], v[172:175], v[228:231], v[4:7]
	v_mfma_f32_16x16x32_bf16 v[0:3], v[180:183], v[228:231], v[0:3]
	s_setprio 0
	s_barrier
	v_add_u32_e32 v156, 0x18000, v222
	v_add_u32_e32 v180, 0x1c000, v222
	ds_read_b128 v[128:131], v156
	ds_read_b128 v[140:143], v156 offset:1024
	ds_read_b128 v[152:155], v156 offset:2048
	ds_read_b128 v[156:159], v156 offset:3072
	ds_read_b128 v[168:171], v180
	ds_read_b128 v[172:175], v180 offset:1024
	ds_read_b128 v[176:179], v180 offset:2048
	ds_read_b128 v[180:183], v180 offset:3072
	ds_read_b128 v[184:187], v223 offset:32768
	ds_read_b128 v[188:191], v223 offset:33792
	ds_read_b128 v[192:195], v223 offset:34816
	ds_read_b128 v[196:199], v223 offset:35840
	ds_read_b128 v[200:203], v223 offset:36864
	ds_read_b128 v[204:207], v223 offset:37888
	ds_read_b128 v[224:227], v223 offset:38912
	ds_read_b128 v[228:231], v223 offset:39936
	s_add_i32 s13, s13, 0x80000
	s_mov_b32 m0, s82
	s_nop 0
	buffer_load_dwordx4 v220, s[64:67], s13 offen lds
	s_nop 0
	s_mov_b32 m0, s83
	s_nop 0
	buffer_load_dwordx4 v221, s[64:67], s13 offen lds
	s_waitcnt vmcnt(8)
	s_waitcnt lgkmcnt(0)
	s_barrier
	s_setprio 1
	v_mfma_f32_16x16x32_bf16 v[164:167], v[128:131], v[184:187], v[164:167]
	v_mfma_f32_16x16x32_bf16 v[160:163], v[152:155], v[184:187], v[160:163]
	v_mfma_f32_16x16x32_bf16 v[136:139], v[128:131], v[192:195], v[136:139]
	v_mfma_f32_16x16x32_bf16 v[132:135], v[152:155], v[192:195], v[132:135]
	v_mfma_f32_16x16x32_bf16 v[116:119], v[128:131], v[200:203], v[116:119]
	v_mfma_f32_16x16x32_bf16 v[112:115], v[152:155], v[200:203], v[112:115]
	v_mfma_f32_16x16x32_bf16 v[76:79], v[128:131], v[224:227], v[76:79]
	v_mfma_f32_16x16x32_bf16 v[72:75], v[152:155], v[224:227], v[72:75]
	v_mfma_f32_16x16x32_bf16 v[164:167], v[140:143], v[188:191], v[164:167]
	v_mfma_f32_16x16x32_bf16 v[160:163], v[156:159], v[188:191], v[160:163]
	v_mfma_f32_16x16x32_bf16 v[136:139], v[140:143], v[196:199], v[136:139]
	v_mfma_f32_16x16x32_bf16 v[132:135], v[156:159], v[196:199], v[132:135]
	v_mfma_f32_16x16x32_bf16 v[116:119], v[140:143], v[204:207], v[116:119]
	v_mfma_f32_16x16x32_bf16 v[112:115], v[156:159], v[204:207], v[112:115]
	v_mfma_f32_16x16x32_bf16 v[76:79], v[140:143], v[228:231], v[76:79]
	v_mfma_f32_16x16x32_bf16 v[72:75], v[156:159], v[228:231], v[72:75]
	v_mfma_f32_16x16x32_bf16 v[148:151], v[168:171], v[184:187], v[148:151]
	v_mfma_f32_16x16x32_bf16 v[144:147], v[176:179], v[184:187], v[144:147]
	v_mfma_f32_16x16x32_bf16 v[124:127], v[168:171], v[192:195], v[124:127]
	v_mfma_f32_16x16x32_bf16 v[120:123], v[176:179], v[192:195], v[120:123]
	v_mfma_f32_16x16x32_bf16 v[108:111], v[168:171], v[200:203], v[108:111]
	v_mfma_f32_16x16x32_bf16 v[104:107], v[176:179], v[200:203], v[104:107]
	v_mfma_f32_16x16x32_bf16 v[68:71], v[168:171], v[224:227], v[68:71]
	v_mfma_f32_16x16x32_bf16 v[64:67], v[176:179], v[224:227], v[64:67]
	v_mfma_f32_16x16x32_bf16 v[148:151], v[172:175], v[188:191], v[148:151]
	v_mfma_f32_16x16x32_bf16 v[144:147], v[180:183], v[188:191], v[144:147]
	v_mfma_f32_16x16x32_bf16 v[124:127], v[172:175], v[196:199], v[124:127]
	v_mfma_f32_16x16x32_bf16 v[120:123], v[180:183], v[196:199], v[120:123]
	v_mfma_f32_16x16x32_bf16 v[108:111], v[172:175], v[204:207], v[108:111]
	v_mfma_f32_16x16x32_bf16 v[104:107], v[180:183], v[204:207], v[104:107]
	v_mfma_f32_16x16x32_bf16 v[68:71], v[172:175], v[228:231], v[68:71]
	v_mfma_f32_16x16x32_bf16 v[64:67], v[180:183], v[228:231], v[64:67]
	s_setprio 0
	s_barrier
	ds_read_b128 v[184:187], v223 offset:49152
	ds_read_b128 v[188:191], v223 offset:50176
	ds_read_b128 v[192:195], v223 offset:51200
	ds_read_b128 v[196:199], v223 offset:52224
	ds_read_b128 v[200:203], v223 offset:53248
	ds_read_b128 v[204:207], v223 offset:54272
	ds_read_b128 v[224:227], v223 offset:55296
	ds_read_b128 v[228:231], v223 offset:56320
	s_or_b32 s13, s12, 0x4000
	s_mov_b32 m0, s34
	s_nop 0
	buffer_load_dwordx4 v220, s[48:51], s13 offen lds
	s_add_i32 s12, s12, 0x84000
	s_mov_b32 m0, s84
	s_nop 0
	buffer_load_dwordx4 v221, s[48:51], s13 offen lds
	s_nop 0
	s_mov_b32 m0, s87
	s_nop 0
	buffer_load_dwordx4 v220, s[48:51], s12 offen lds
	s_nop 0
	s_mov_b32 m0, s88
	s_nop 0
	buffer_load_dwordx4 v221, s[48:51], s12 offen lds
	s_nop 0
	s_mov_b32 m0, s85
	s_nop 0
	buffer_load_dwordx4 v220, s[64:67], s11 offen lds
	s_nop 0
	s_mov_b32 m0, s86
	s_nop 0
	buffer_load_dwordx4 v221, s[64:67], s11 offen lds
	s_waitcnt vmcnt(8)
	s_waitcnt lgkmcnt(0)
	s_barrier
	s_setprio 1
	v_mfma_f32_16x16x32_bf16 v[60:63], v[128:131], v[184:187], v[60:63]
	v_mfma_f32_16x16x32_bf16 v[56:59], v[152:155], v[184:187], v[56:59]
	v_mfma_f32_16x16x32_bf16 v[44:47], v[128:131], v[192:195], v[44:47]
	v_mfma_f32_16x16x32_bf16 v[40:43], v[152:155], v[192:195], v[40:43]
	v_mfma_f32_16x16x32_bf16 v[28:31], v[128:131], v[200:203], v[28:31]
	v_mfma_f32_16x16x32_bf16 v[24:27], v[152:155], v[200:203], v[24:27]
	v_mfma_f32_16x16x32_bf16 v[12:15], v[128:131], v[224:227], v[12:15]
	v_mfma_f32_16x16x32_bf16 v[8:11], v[152:155], v[224:227], v[8:11]
	v_mfma_f32_16x16x32_bf16 v[60:63], v[140:143], v[188:191], v[60:63]
	v_mfma_f32_16x16x32_bf16 v[56:59], v[156:159], v[188:191], v[56:59]
	v_mfma_f32_16x16x32_bf16 v[44:47], v[140:143], v[196:199], v[44:47]
	v_mfma_f32_16x16x32_bf16 v[40:43], v[156:159], v[196:199], v[40:43]
	v_mfma_f32_16x16x32_bf16 v[28:31], v[140:143], v[204:207], v[28:31]
	v_mfma_f32_16x16x32_bf16 v[24:27], v[156:159], v[204:207], v[24:27]
	v_mfma_f32_16x16x32_bf16 v[12:15], v[140:143], v[228:231], v[12:15]
	v_mfma_f32_16x16x32_bf16 v[8:11], v[156:159], v[228:231], v[8:11]
	v_mfma_f32_16x16x32_bf16 v[52:55], v[168:171], v[184:187], v[52:55]
	v_mfma_f32_16x16x32_bf16 v[48:51], v[176:179], v[184:187], v[48:51]
	v_mfma_f32_16x16x32_bf16 v[36:39], v[168:171], v[192:195], v[36:39]
	v_mfma_f32_16x16x32_bf16 v[32:35], v[176:179], v[192:195], v[32:35]
	v_mfma_f32_16x16x32_bf16 v[20:23], v[168:171], v[200:203], v[20:23]
	v_mfma_f32_16x16x32_bf16 v[16:19], v[176:179], v[200:203], v[16:19]
	v_mfma_f32_16x16x32_bf16 v[4:7], v[168:171], v[224:227], v[4:7]
	v_mfma_f32_16x16x32_bf16 v[0:3], v[176:179], v[224:227], v[0:3]
	v_mfma_f32_16x16x32_bf16 v[52:55], v[172:175], v[188:191], v[52:55]
	v_mfma_f32_16x16x32_bf16 v[48:51], v[180:183], v[188:191], v[48:51]
	v_mfma_f32_16x16x32_bf16 v[36:39], v[172:175], v[196:199], v[36:39]
	v_mfma_f32_16x16x32_bf16 v[32:35], v[180:183], v[196:199], v[32:35]
	v_mfma_f32_16x16x32_bf16 v[20:23], v[172:175], v[204:207], v[20:23]
	v_mfma_f32_16x16x32_bf16 v[16:19], v[180:183], v[204:207], v[16:19]
	v_mfma_f32_16x16x32_bf16 v[4:7], v[172:175], v[228:231], v[4:7]
	v_mfma_f32_16x16x32_bf16 v[0:3], v[180:183], v[228:231], v[0:3]
	s_setprio 0
	s_barrier
	s_add_i32 s10, s10, 2
	s_add_i32 s8, s8, 0x8000
	s_add_i32 s9, s9, 0x8000
	s_cmp_gt_u32 s10, 29
	s_cbranch_scc0 .LBB0_691

.Lnb_p5:
	s_add_i32 s53, s37, 0xfff84000
	s_cmp_eq_u32 s52, 28
	s_cselect_b32 s56, s4, s53
	s_cselect_b32 s55, s5, s51
	s_or_b32 s53, s56, 0x4000
	s_mov_b32 m0, s41
	s_nop 0
	buffer_load_dwordx4 v166, s[24:27], s37 offen lds
	s_nop 0
	s_mov_b32 m0, s42
	s_nop 0
	buffer_load_dwordx4 v167, s[24:27], s37 offen lds
	s_waitcnt vmcnt(24)
	s_waitcnt lgkmcnt(0)
	s_barrier
	s_setprio 1
	v_mfma_f32_16x16x32_bf16 v[148:151], v[152:155], v[190:193], 0
	v_mfma_f32_16x16x32_bf16 v[140:143], v[160:163], v[190:193], 0
	v_mfma_f32_16x16x32_bf16 v[132:135], v[152:155], v[198:201], 0
	v_mfma_f32_16x16x32_bf16 v[124:127], v[160:163], v[198:201], 0
	v_mfma_f32_16x16x32_bf16 v[116:119], v[152:155], v[220:223], 0
	v_mfma_f32_16x16x32_bf16 v[108:111], v[160:163], v[220:223], 0
	v_mfma_f32_16x16x32_bf16 v[76:79], v[152:155], v[228:231], 0
	v_mfma_f32_16x16x32_bf16 v[68:71], v[160:163], v[228:231], 0
	v_mfma_f32_16x16x32_bf16 v[148:151], v[156:159], v[194:197], v[148:151]
	v_mfma_f32_16x16x32_bf16 v[140:143], v[170:173], v[194:197], v[140:143]
	v_mfma_f32_16x16x32_bf16 v[132:135], v[156:159], v[202:205], v[132:135]
	v_mfma_f32_16x16x32_bf16 v[124:127], v[170:173], v[202:205], v[124:127]
	v_mfma_f32_16x16x32_bf16 v[116:119], v[156:159], v[224:227], v[116:119]
	v_mfma_f32_16x16x32_bf16 v[108:111], v[170:173], v[224:227], v[108:111]
	v_mfma_f32_16x16x32_bf16 v[76:79], v[156:159], v[240:243], v[76:79]
	v_mfma_f32_16x16x32_bf16 v[68:71], v[170:173], v[240:243], v[68:71]
	v_mfma_f32_16x16x32_bf16 v[144:147], v[174:177], v[190:193], 0
	v_mfma_f32_16x16x32_bf16 v[136:139], v[182:185], v[190:193], 0
	v_mfma_f32_16x16x32_bf16 v[128:131], v[174:177], v[198:201], 0
	v_mfma_f32_16x16x32_bf16 v[120:123], v[182:185], v[198:201], 0
	v_mfma_f32_16x16x32_bf16 v[112:115], v[174:177], v[220:223], 0
	v_mfma_f32_16x16x32_bf16 v[104:107], v[182:185], v[220:223], 0
	v_mfma_f32_16x16x32_bf16 v[72:75], v[174:177], v[228:231], 0
	v_mfma_f32_16x16x32_bf16 v[64:67], v[182:185], v[228:231], 0
	v_mfma_f32_16x16x32_bf16 v[144:147], v[178:181], v[194:197], v[144:147]
	v_mfma_f32_16x16x32_bf16 v[136:139], v[186:189], v[194:197], v[136:139]
	v_mfma_f32_16x16x32_bf16 v[128:131], v[178:181], v[202:205], v[128:131]
	v_mfma_f32_16x16x32_bf16 v[120:123], v[186:189], v[202:205], v[120:123]
	v_mfma_f32_16x16x32_bf16 v[112:115], v[178:181], v[224:227], v[112:115]
	v_mfma_f32_16x16x32_bf16 v[104:107], v[186:189], v[224:227], v[104:107]
	v_mfma_f32_16x16x32_bf16 v[72:75], v[178:181], v[240:243], v[72:75]
	v_mfma_f32_16x16x32_bf16 v[64:67], v[186:189], v[240:243], v[64:67]
	s_setprio 0
	s_barrier
	ds_read_b128 v[190:193], v169 offset:16384
	ds_read_b128 v[194:197], v169 offset:17408
	ds_read_b128 v[198:201], v169 offset:18432
	ds_read_b128 v[202:205], v169 offset:19456
	ds_read_b128 v[220:223], v169 offset:20480
	ds_read_b128 v[224:227], v169 offset:21504
	ds_read_b128 v[228:231], v169 offset:22528
	ds_read_b128 v[240:243], v169 offset:23552
	s_mov_b32 m0, s7
	s_nop 0
	buffer_load_dwordx4 v166, s[28:31], s55 offen lds
	s_add_i32 s57, s55, 0x80000
	s_mov_b32 m0, s8
	s_nop 0
	buffer_load_dwordx4 v167, s[28:31], s55 offen lds
	s_nop 0
	s_mov_b32 m0, s9
	s_nop 0
	buffer_load_dwordx4 v166, s[28:31], s57 offen lds
	s_nop 0
	s_mov_b32 m0, s10
	s_nop 0
	buffer_load_dwordx4 v167, s[28:31], s57 offen lds
	s_nop 0
	s_mov_b32 m0, s6
	s_nop 0
	buffer_load_dwordx4 v166, s[24:27], s56 offen lds
	s_nop 0
	s_mov_b32 m0, s11
	s_nop 0
	buffer_load_dwordx4 v167, s[24:27], s56 offen lds
	s_waitcnt vmcnt(24)
	s_waitcnt lgkmcnt(0)
	s_barrier
	s_setprio 1
	v_mfma_f32_16x16x32_bf16 v[60:63], v[152:155], v[190:193], 0
	v_mfma_f32_16x16x32_bf16 v[52:55], v[160:163], v[190:193], 0
	v_mfma_f32_16x16x32_bf16 v[44:47], v[152:155], v[198:201], 0
	v_mfma_f32_16x16x32_bf16 v[36:39], v[160:163], v[198:201], 0
	v_mfma_f32_16x16x32_bf16 v[28:31], v[152:155], v[220:223], 0
	v_mfma_f32_16x16x32_bf16 v[20:23], v[160:163], v[220:223], 0
	v_mfma_f32_16x16x32_bf16 v[12:15], v[152:155], v[228:231], 0
	v_mfma_f32_16x16x32_bf16 v[4:7], v[160:163], v[228:231], 0
	v_mfma_f32_16x16x32_bf16 v[60:63], v[156:159], v[194:197], v[60:63]
	v_mfma_f32_16x16x32_bf16 v[52:55], v[170:173], v[194:197], v[52:55]
	v_mfma_f32_16x16x32_bf16 v[44:47], v[156:159], v[202:205], v[44:47]
	v_mfma_f32_16x16x32_bf16 v[36:39], v[170:173], v[202:205], v[36:39]
	v_mfma_f32_16x16x32_bf16 v[28:31], v[156:159], v[224:227], v[28:31]
	v_mfma_f32_16x16x32_bf16 v[20:23], v[170:173], v[224:227], v[20:23]
	v_mfma_f32_16x16x32_bf16 v[12:15], v[156:159], v[240:243], v[12:15]
	v_mfma_f32_16x16x32_bf16 v[4:7], v[170:173], v[240:243], v[4:7]
	v_mfma_f32_16x16x32_bf16 v[56:59], v[174:177], v[190:193], 0
	v_mfma_f32_16x16x32_bf16 v[48:51], v[182:185], v[190:193], 0
	v_mfma_f32_16x16x32_bf16 v[40:43], v[174:177], v[198:201], 0
	v_mfma_f32_16x16x32_bf16 v[32:35], v[182:185], v[198:201], 0
	v_mfma_f32_16x16x32_bf16 v[24:27], v[174:177], v[220:223], 0
	v_mfma_f32_16x16x32_bf16 v[16:19], v[182:185], v[220:223], 0
	v_mfma_f32_16x16x32_bf16 v[8:11], v[174:177], v[228:231], 0
	v_mfma_f32_16x16x32_bf16 v[0:3], v[182:185], v[228:231], 0
	v_mfma_f32_16x16x32_bf16 v[56:59], v[178:181], v[194:197], v[56:59]
	v_mfma_f32_16x16x32_bf16 v[48:51], v[186:189], v[194:197], v[48:51]
	v_mfma_f32_16x16x32_bf16 v[40:43], v[178:181], v[202:205], v[40:43]
	v_mfma_f32_16x16x32_bf16 v[32:35], v[186:189], v[202:205], v[32:35]
	v_mfma_f32_16x16x32_bf16 v[24:27], v[178:181], v[224:227], v[24:27]
	v_mfma_f32_16x16x32_bf16 v[16:19], v[186:189], v[224:227], v[16:19]
	v_mfma_f32_16x16x32_bf16 v[8:11], v[178:181], v[240:243], v[8:11]
	v_mfma_f32_16x16x32_bf16 v[0:3], v[186:189], v[240:243], v[0:3]
	s_setprio 0
	s_barrier
	v_add_u32_e32 v164, 0x18000, v168
	ds_read_b128 v[152:155], v164
	ds_read_b128 v[156:159], v164 offset:1024
	ds_read_b128 v[160:163], v164 offset:2048
	ds_read_b128 v[170:173], v164 offset:3072
	v_add_u32_e32 v164, 0x1c000, v168
	ds_read_b128 v[174:177], v164
	ds_read_b128 v[178:181], v164 offset:1024
	ds_read_b128 v[182:185], v164 offset:2048
	ds_read_b128 v[186:189], v164 offset:3072
	ds_read_b128 v[190:193], v169 offset:32768
	ds_read_b128 v[194:197], v169 offset:33792
	ds_read_b128 v[198:201], v169 offset:34816
	ds_read_b128 v[202:205], v169 offset:35840
	ds_read_b128 v[220:223], v169 offset:36864
	ds_read_b128 v[224:227], v169 offset:37888
	ds_read_b128 v[228:231], v169 offset:38912
	ds_read_b128 v[240:243], v169 offset:39936
	s_add_i32 s56, s56, 0x80000
	s_mov_b32 m0, s12
	s_nop 0
	buffer_load_dwordx4 v166, s[24:27], s56 offen lds
	s_nop 0
	s_mov_b32 m0, s13
	s_nop 0
	buffer_load_dwordx4 v167, s[24:27], s56 offen lds
	s_waitcnt vmcnt(8)
	s_waitcnt lgkmcnt(0)
	s_barrier
	s_setprio 1
	v_mfma_f32_16x16x32_bf16 v[148:151], v[152:155], v[190:193], v[148:151]
	v_mfma_f32_16x16x32_bf16 v[140:143], v[160:163], v[190:193], v[140:143]
	v_mfma_f32_16x16x32_bf16 v[132:135], v[152:155], v[198:201], v[132:135]
	v_mfma_f32_16x16x32_bf16 v[124:127], v[160:163], v[198:201], v[124:127]
	v_mfma_f32_16x16x32_bf16 v[116:119], v[152:155], v[220:223], v[116:119]
	v_mfma_f32_16x16x32_bf16 v[108:111], v[160:163], v[220:223], v[108:111]
	v_mfma_f32_16x16x32_bf16 v[76:79], v[152:155], v[228:231], v[76:79]
	v_mfma_f32_16x16x32_bf16 v[68:71], v[160:163], v[228:231], v[68:71]
	v_mfma_f32_16x16x32_bf16 v[148:151], v[156:159], v[194:197], v[148:151]
	v_mfma_f32_16x16x32_bf16 v[140:143], v[170:173], v[194:197], v[140:143]
	v_mfma_f32_16x16x32_bf16 v[132:135], v[156:159], v[202:205], v[132:135]
	v_mfma_f32_16x16x32_bf16 v[124:127], v[170:173], v[202:205], v[124:127]
	v_mfma_f32_16x16x32_bf16 v[116:119], v[156:159], v[224:227], v[116:119]
	v_mfma_f32_16x16x32_bf16 v[108:111], v[170:173], v[224:227], v[108:111]
	v_mfma_f32_16x16x32_bf16 v[76:79], v[156:159], v[240:243], v[76:79]
	v_mfma_f32_16x16x32_bf16 v[68:71], v[170:173], v[240:243], v[68:71]
	v_mfma_f32_16x16x32_bf16 v[144:147], v[174:177], v[190:193], v[144:147]
	v_mfma_f32_16x16x32_bf16 v[136:139], v[182:185], v[190:193], v[136:139]
	v_mfma_f32_16x16x32_bf16 v[128:131], v[174:177], v[198:201], v[128:131]
	v_mfma_f32_16x16x32_bf16 v[120:123], v[182:185], v[198:201], v[120:123]
	v_mfma_f32_16x16x32_bf16 v[112:115], v[174:177], v[220:223], v[112:115]
	v_mfma_f32_16x16x32_bf16 v[104:107], v[182:185], v[220:223], v[104:107]
	v_mfma_f32_16x16x32_bf16 v[72:75], v[174:177], v[228:231], v[72:75]
	v_mfma_f32_16x16x32_bf16 v[64:67], v[182:185], v[228:231], v[64:67]
	v_mfma_f32_16x16x32_bf16 v[144:147], v[178:181], v[194:197], v[144:147]
	v_mfma_f32_16x16x32_bf16 v[136:139], v[186:189], v[194:197], v[136:139]
	v_mfma_f32_16x16x32_bf16 v[128:131], v[178:181], v[202:205], v[128:131]
	v_mfma_f32_16x16x32_bf16 v[120:123], v[186:189], v[202:205], v[120:123]
	v_mfma_f32_16x16x32_bf16 v[112:115], v[178:181], v[224:227], v[112:115]
	v_mfma_f32_16x16x32_bf16 v[104:107], v[186:189], v[224:227], v[104:107]
	v_mfma_f32_16x16x32_bf16 v[72:75], v[178:181], v[240:243], v[72:75]
	v_mfma_f32_16x16x32_bf16 v[64:67], v[186:189], v[240:243], v[64:67]
	s_setprio 0
	s_barrier
	ds_read_b128 v[190:193], v169 offset:49152
	ds_read_b128 v[194:197], v169 offset:50176
	ds_read_b128 v[198:201], v169 offset:51200
	ds_read_b128 v[202:205], v169 offset:52224
	ds_read_b128 v[220:223], v169 offset:53248
	ds_read_b128 v[224:227], v169 offset:54272
	ds_read_b128 v[228:231], v169 offset:55296
	ds_read_b128 v[240:243], v169 offset:56320
	s_or_b32 s56, s55, 0x4000
	s_mov_b32 m0, s16
	s_nop 0
	buffer_load_dwordx4 v166, s[28:31], s56 offen lds
	s_add_i32 s55, s55, 0x84000
	s_mov_b32 m0, s17
	s_nop 0
	buffer_load_dwordx4 v167, s[28:31], s56 offen lds
	s_nop 0
	s_mov_b32 m0, s34
	s_nop 0
	buffer_load_dwordx4 v166, s[28:31], s55 offen lds
	s_nop 0
	s_mov_b32 m0, s40
	s_nop 0
	buffer_load_dwordx4 v167, s[28:31], s55 offen lds
	s_nop 0
	s_mov_b32 m0, s18
	s_nop 0
	buffer_load_dwordx4 v166, s[24:27], s53 offen lds
	s_nop 0
	s_mov_b32 m0, s19
	s_nop 0
	buffer_load_dwordx4 v167, s[24:27], s53 offen lds
	s_waitcnt vmcnt(8)
	s_waitcnt lgkmcnt(0)
	s_barrier
	s_setprio 1
	v_mfma_f32_16x16x32_bf16 v[60:63], v[152:155], v[190:193], v[60:63]
	v_mfma_f32_16x16x32_bf16 v[52:55], v[160:163], v[190:193], v[52:55]
	v_mfma_f32_16x16x32_bf16 v[44:47], v[152:155], v[198:201], v[44:47]
	v_mfma_f32_16x16x32_bf16 v[36:39], v[160:163], v[198:201], v[36:39]
	v_mfma_f32_16x16x32_bf16 v[28:31], v[152:155], v[220:223], v[28:31]
	v_mfma_f32_16x16x32_bf16 v[20:23], v[160:163], v[220:223], v[20:23]
	v_mfma_f32_16x16x32_bf16 v[12:15], v[152:155], v[228:231], v[12:15]
	v_mfma_f32_16x16x32_bf16 v[4:7], v[160:163], v[228:231], v[4:7]
	v_mfma_f32_16x16x32_bf16 v[60:63], v[156:159], v[194:197], v[60:63]
	v_mfma_f32_16x16x32_bf16 v[52:55], v[170:173], v[194:197], v[52:55]
	v_mfma_f32_16x16x32_bf16 v[44:47], v[156:159], v[202:205], v[44:47]
	v_mfma_f32_16x16x32_bf16 v[36:39], v[170:173], v[202:205], v[36:39]
	v_mfma_f32_16x16x32_bf16 v[28:31], v[156:159], v[224:227], v[28:31]
	v_mfma_f32_16x16x32_bf16 v[20:23], v[170:173], v[224:227], v[20:23]
	v_mfma_f32_16x16x32_bf16 v[12:15], v[156:159], v[240:243], v[12:15]
	v_mfma_f32_16x16x32_bf16 v[4:7], v[170:173], v[240:243], v[4:7]
	v_mfma_f32_16x16x32_bf16 v[56:59], v[174:177], v[190:193], v[56:59]
	v_mfma_f32_16x16x32_bf16 v[48:51], v[182:185], v[190:193], v[48:51]
	v_mfma_f32_16x16x32_bf16 v[40:43], v[174:177], v[198:201], v[40:43]
	v_mfma_f32_16x16x32_bf16 v[32:35], v[182:185], v[198:201], v[32:35]
	v_mfma_f32_16x16x32_bf16 v[24:27], v[174:177], v[220:223], v[24:27]
	v_mfma_f32_16x16x32_bf16 v[16:19], v[182:185], v[220:223], v[16:19]
	v_mfma_f32_16x16x32_bf16 v[8:11], v[174:177], v[228:231], v[8:11]
	v_mfma_f32_16x16x32_bf16 v[0:3], v[182:185], v[228:231], v[0:3]
	v_mfma_f32_16x16x32_bf16 v[56:59], v[178:181], v[194:197], v[56:59]
	v_mfma_f32_16x16x32_bf16 v[48:51], v[186:189], v[194:197], v[48:51]
	v_mfma_f32_16x16x32_bf16 v[40:43], v[178:181], v[202:205], v[40:43]
	v_mfma_f32_16x16x32_bf16 v[32:35], v[186:189], v[202:205], v[32:35]
	v_mfma_f32_16x16x32_bf16 v[24:27], v[178:181], v[224:227], v[24:27]
	v_mfma_f32_16x16x32_bf16 v[16:19], v[186:189], v[224:227], v[16:19]
	v_mfma_f32_16x16x32_bf16 v[8:11], v[178:181], v[240:243], v[8:11]
	v_mfma_f32_16x16x32_bf16 v[0:3], v[186:189], v[240:243], v[0:3]
	s_setprio 0
	s_barrier
	s_add_i32 s52, s52, 2
	s_add_i32 s37, s37, 0x8000
	s_add_i32 s51, s51, 0x8000
.LBB0_795:
	v_add_u32_e32 v164, 0x10000, v168
	ds_read_b128 v[152:155], v164
	ds_read_b128 v[156:159], v164 offset:1024
	ds_read_b128 v[160:163], v164 offset:2048
	ds_read_b128 v[170:173], v164 offset:3072
	v_add_u32_e32 v164, 0x14000, v168
	ds_read_b128 v[174:177], v164
	ds_read_b128 v[178:181], v164 offset:1024
	ds_read_b128 v[182:185], v164 offset:2048
	ds_read_b128 v[186:189], v164 offset:3072
	s_add_i32 s53, s37, 0xfff84000
	s_cmp_eq_u32 s52, 28
	s_cselect_b32 s56, s4, s53
	s_cselect_b32 s55, s5, s51
	s_or_b32 s53, s56, 0x4000
	ds_read_b128 v[190:193], v169
	ds_read_b128 v[194:197], v169 offset:1024
	ds_read_b128 v[198:201], v169 offset:2048
	ds_read_b128 v[202:205], v169 offset:3072
	ds_read_b128 v[220:223], v169 offset:4096
	ds_read_b128 v[224:227], v169 offset:5120
	ds_read_b128 v[228:231], v169 offset:6144
	ds_read_b128 v[240:243], v169 offset:7168
	s_mov_b32 m0, s41
	s_nop 0
	buffer_load_dwordx4 v166, s[24:27], s37 offen lds
	s_nop 0
	s_mov_b32 m0, s42
	s_nop 0
	buffer_load_dwordx4 v167, s[24:27], s37 offen lds
	s_waitcnt vmcnt(8)
	s_waitcnt lgkmcnt(0)
	s_barrier
	s_setprio 1
	v_mfma_f32_16x16x32_bf16 v[148:151], v[152:155], v[190:193], v[148:151]
	v_mfma_f32_16x16x32_bf16 v[140:143], v[160:163], v[190:193], v[140:143]
	v_mfma_f32_16x16x32_bf16 v[132:135], v[152:155], v[198:201], v[132:135]
	v_mfma_f32_16x16x32_bf16 v[124:127], v[160:163], v[198:201], v[124:127]
	v_mfma_f32_16x16x32_bf16 v[116:119], v[152:155], v[220:223], v[116:119]
	v_mfma_f32_16x16x32_bf16 v[108:111], v[160:163], v[220:223], v[108:111]
	v_mfma_f32_16x16x32_bf16 v[76:79], v[152:155], v[228:231], v[76:79]
	v_mfma_f32_16x16x32_bf16 v[68:71], v[160:163], v[228:231], v[68:71]
	v_mfma_f32_16x16x32_bf16 v[148:151], v[156:159], v[194:197], v[148:151]
	v_mfma_f32_16x16x32_bf16 v[140:143], v[170:173], v[194:197], v[140:143]
	v_mfma_f32_16x16x32_bf16 v[132:135], v[156:159], v[202:205], v[132:135]
	v_mfma_f32_16x16x32_bf16 v[124:127], v[170:173], v[202:205], v[124:127]
	v_mfma_f32_16x16x32_bf16 v[116:119], v[156:159], v[224:227], v[116:119]
	v_mfma_f32_16x16x32_bf16 v[108:111], v[170:173], v[224:227], v[108:111]
	v_mfma_f32_16x16x32_bf16 v[76:79], v[156:159], v[240:243], v[76:79]
	v_mfma_f32_16x16x32_bf16 v[68:71], v[170:173], v[240:243], v[68:71]
	v_mfma_f32_16x16x32_bf16 v[144:147], v[174:177], v[190:193], v[144:147]
	v_mfma_f32_16x16x32_bf16 v[136:139], v[182:185], v[190:193], v[136:139]
	v_mfma_f32_16x16x32_bf16 v[128:131], v[174:177], v[198:201], v[128:131]
	v_mfma_f32_16x16x32_bf16 v[120:123], v[182:185], v[198:201], v[120:123]
	v_mfma_f32_16x16x32_bf16 v[112:115], v[174:177], v[220:223], v[112:115]
	v_mfma_f32_16x16x32_bf16 v[104:107], v[182:185], v[220:223], v[104:107]
	v_mfma_f32_16x16x32_bf16 v[72:75], v[174:177], v[228:231], v[72:75]
	v_mfma_f32_16x16x32_bf16 v[64:67], v[182:185], v[228:231], v[64:67]
	v_mfma_f32_16x16x32_bf16 v[144:147], v[178:181], v[194:197], v[144:147]
	v_mfma_f32_16x16x32_bf16 v[136:139], v[186:189], v[194:197], v[136:139]
	v_mfma_f32_16x16x32_bf16 v[128:131], v[178:181], v[202:205], v[128:131]
	v_mfma_f32_16x16x32_bf16 v[120:123], v[186:189], v[202:205], v[120:123]
	v_mfma_f32_16x16x32_bf16 v[112:115], v[178:181], v[224:227], v[112:115]
	v_mfma_f32_16x16x32_bf16 v[104:107], v[186:189], v[224:227], v[104:107]
	v_mfma_f32_16x16x32_bf16 v[72:75], v[178:181], v[240:243], v[72:75]
	v_mfma_f32_16x16x32_bf16 v[64:67], v[186:189], v[240:243], v[64:67]
	s_setprio 0
	s_barrier
	ds_read_b128 v[190:193], v169 offset:16384
	ds_read_b128 v[194:197], v169 offset:17408
	ds_read_b128 v[198:201], v169 offset:18432
	ds_read_b128 v[202:205], v169 offset:19456
	ds_read_b128 v[220:223], v169 offset:20480
	ds_read_b128 v[224:227], v169 offset:21504
	ds_read_b128 v[228:231], v169 offset:22528
	ds_read_b128 v[240:243], v169 offset:23552
	s_mov_b32 m0, s7
	s_nop 0
	buffer_load_dwordx4 v166, s[28:31], s55 offen lds
	s_add_i32 s57, s55, 0x80000
	s_mov_b32 m0, s8
	s_nop 0
	buffer_load_dwordx4 v167, s[28:31], s55 offen lds
	s_nop 0
	s_mov_b32 m0, s9
	s_nop 0
	buffer_load_dwordx4 v166, s[28:31], s57 offen lds
	s_nop 0
	s_mov_b32 m0, s10
	s_nop 0
	buffer_load_dwordx4 v167, s[28:31], s57 offen lds
	s_nop 0
	s_mov_b32 m0, s6
	s_nop 0
	buffer_load_dwordx4 v166, s[24:27], s56 offen lds
	s_nop 0
	s_mov_b32 m0, s11
	s_nop 0
	buffer_load_dwordx4 v167, s[24:27], s56 offen lds
	s_waitcnt vmcnt(8)
	s_waitcnt lgkmcnt(0)
	s_barrier
	s_setprio 1
	v_mfma_f32_16x16x32_bf16 v[60:63], v[152:155], v[190:193], v[60:63]
	v_mfma_f32_16x16x32_bf16 v[52:55], v[160:163], v[190:193], v[52:55]
	v_mfma_f32_16x16x32_bf16 v[44:47], v[152:155], v[198:201], v[44:47]
	v_mfma_f32_16x16x32_bf16 v[36:39], v[160:163], v[198:201], v[36:39]
	v_mfma_f32_16x16x32_bf16 v[28:31], v[152:155], v[220:223], v[28:31]
	v_mfma_f32_16x16x32_bf16 v[20:23], v[160:163], v[220:223], v[20:23]
	v_mfma_f32_16x16x32_bf16 v[12:15], v[152:155], v[228:231], v[12:15]
	v_mfma_f32_16x16x32_bf16 v[4:7], v[160:163], v[228:231], v[4:7]
	v_mfma_f32_16x16x32_bf16 v[60:63], v[156:159], v[194:197], v[60:63]
	v_mfma_f32_16x16x32_bf16 v[52:55], v[170:173], v[194:197], v[52:55]
	v_mfma_f32_16x16x32_bf16 v[44:47], v[156:159], v[202:205], v[44:47]
	v_mfma_f32_16x16x32_bf16 v[36:39], v[170:173], v[202:205], v[36:39]
	v_mfma_f32_16x16x32_bf16 v[28:31], v[156:159], v[224:227], v[28:31]
	v_mfma_f32_16x16x32_bf16 v[20:23], v[170:173], v[224:227], v[20:23]
	v_mfma_f32_16x16x32_bf16 v[12:15], v[156:159], v[240:243], v[12:15]
	v_mfma_f32_16x16x32_bf16 v[4:7], v[170:173], v[240:243], v[4:7]
	v_mfma_f32_16x16x32_bf16 v[56:59], v[174:177], v[190:193], v[56:59]
	v_mfma_f32_16x16x32_bf16 v[48:51], v[182:185], v[190:193], v[48:51]
	v_mfma_f32_16x16x32_bf16 v[40:43], v[174:177], v[198:201], v[40:43]
	v_mfma_f32_16x16x32_bf16 v[32:35], v[182:185], v[198:201], v[32:35]
	v_mfma_f32_16x16x32_bf16 v[24:27], v[174:177], v[220:223], v[24:27]
	v_mfma_f32_16x16x32_bf16 v[16:19], v[182:185], v[220:223], v[16:19]
	v_mfma_f32_16x16x32_bf16 v[8:11], v[174:177], v[228:231], v[8:11]
	v_mfma_f32_16x16x32_bf16 v[0:3], v[182:185], v[228:231], v[0:3]
	v_mfma_f32_16x16x32_bf16 v[56:59], v[178:181], v[194:197], v[56:59]
	v_mfma_f32_16x16x32_bf16 v[48:51], v[186:189], v[194:197], v[48:51]
	v_mfma_f32_16x16x32_bf16 v[40:43], v[178:181], v[202:205], v[40:43]
	v_mfma_f32_16x16x32_bf16 v[32:35], v[186:189], v[202:205], v[32:35]
	v_mfma_f32_16x16x32_bf16 v[24:27], v[178:181], v[224:227], v[24:27]
	v_mfma_f32_16x16x32_bf16 v[16:19], v[186:189], v[224:227], v[16:19]
	v_mfma_f32_16x16x32_bf16 v[8:11], v[178:181], v[240:243], v[8:11]
	v_mfma_f32_16x16x32_bf16 v[0:3], v[186:189], v[240:243], v[0:3]
	s_setprio 0
	s_barrier
	v_add_u32_e32 v164, 0x18000, v168
	ds_read_b128 v[152:155], v164
	ds_read_b128 v[156:159], v164 offset:1024
	ds_read_b128 v[160:163], v164 offset:2048
	ds_read_b128 v[170:173], v164 offset:3072
	v_add_u32_e32 v164, 0x1c000, v168
	ds_read_b128 v[174:177], v164
	ds_read_b128 v[178:181], v164 offset:1024
	ds_read_b128 v[182:185], v164 offset:2048
	ds_read_b128 v[186:189], v164 offset:3072
	ds_read_b128 v[190:193], v169 offset:32768
	ds_read_b128 v[194:197], v169 offset:33792
	ds_read_b128 v[198:201], v169 offset:34816
	ds_read_b128 v[202:205], v169 offset:35840
	ds_read_b128 v[220:223], v169 offset:36864
	ds_read_b128 v[224:227], v169 offset:37888
	ds_read_b128 v[228:231], v169 offset:38912
	ds_read_b128 v[240:243], v169 offset:39936
	s_add_i32 s56, s56, 0x80000
	s_mov_b32 m0, s12
	s_nop 0
	buffer_load_dwordx4 v166, s[24:27], s56 offen lds
	s_nop 0
	s_mov_b32 m0, s13
	s_nop 0
	buffer_load_dwordx4 v167, s[24:27], s56 offen lds
	s_waitcnt vmcnt(8)
	s_waitcnt lgkmcnt(0)
	s_barrier
	s_setprio 1
	v_mfma_f32_16x16x32_bf16 v[148:151], v[152:155], v[190:193], v[148:151]
	v_mfma_f32_16x16x32_bf16 v[140:143], v[160:163], v[190:193], v[140:143]
	v_mfma_f32_16x16x32_bf16 v[132:135], v[152:155], v[198:201], v[132:135]
	v_mfma_f32_16x16x32_bf16 v[124:127], v[160:163], v[198:201], v[124:127]
	v_mfma_f32_16x16x32_bf16 v[116:119], v[152:155], v[220:223], v[116:119]
	v_mfma_f32_16x16x32_bf16 v[108:111], v[160:163], v[220:223], v[108:111]
	v_mfma_f32_16x16x32_bf16 v[76:79], v[152:155], v[228:231], v[76:79]
	v_mfma_f32_16x16x32_bf16 v[68:71], v[160:163], v[228:231], v[68:71]
	v_mfma_f32_16x16x32_bf16 v[148:151], v[156:159], v[194:197], v[148:151]
	v_mfma_f32_16x16x32_bf16 v[140:143], v[170:173], v[194:197], v[140:143]
	v_mfma_f32_16x16x32_bf16 v[132:135], v[156:159], v[202:205], v[132:135]
	v_mfma_f32_16x16x32_bf16 v[124:127], v[170:173], v[202:205], v[124:127]
	v_mfma_f32_16x16x32_bf16 v[116:119], v[156:159], v[224:227], v[116:119]
	v_mfma_f32_16x16x32_bf16 v[108:111], v[170:173], v[224:227], v[108:111]
	v_mfma_f32_16x16x32_bf16 v[76:79], v[156:159], v[240:243], v[76:79]
	v_mfma_f32_16x16x32_bf16 v[68:71], v[170:173], v[240:243], v[68:71]
	v_mfma_f32_16x16x32_bf16 v[144:147], v[174:177], v[190:193], v[144:147]
	v_mfma_f32_16x16x32_bf16 v[136:139], v[182:185], v[190:193], v[136:139]
	v_mfma_f32_16x16x32_bf16 v[128:131], v[174:177], v[198:201], v[128:131]
	v_mfma_f32_16x16x32_bf16 v[120:123], v[182:185], v[198:201], v[120:123]
	v_mfma_f32_16x16x32_bf16 v[112:115], v[174:177], v[220:223], v[112:115]
	v_mfma_f32_16x16x32_bf16 v[104:107], v[182:185], v[220:223], v[104:107]
	v_mfma_f32_16x16x32_bf16 v[72:75], v[174:177], v[228:231], v[72:75]
	v_mfma_f32_16x16x32_bf16 v[64:67], v[182:185], v[228:231], v[64:67]
	v_mfma_f32_16x16x32_bf16 v[144:147], v[178:181], v[194:197], v[144:147]
	v_mfma_f32_16x16x32_bf16 v[136:139], v[186:189], v[194:197], v[136:139]
	v_mfma_f32_16x16x32_bf16 v[128:131], v[178:181], v[202:205], v[128:131]
	v_mfma_f32_16x16x32_bf16 v[120:123], v[186:189], v[202:205], v[120:123]
	v_mfma_f32_16x16x32_bf16 v[112:115], v[178:181], v[224:227], v[112:115]
	v_mfma_f32_16x16x32_bf16 v[104:107], v[186:189], v[224:227], v[104:107]
	v_mfma_f32_16x16x32_bf16 v[72:75], v[178:181], v[240:243], v[72:75]
	v_mfma_f32_16x16x32_bf16 v[64:67], v[186:189], v[240:243], v[64:67]
	s_setprio 0
	s_barrier
	ds_read_b128 v[190:193], v169 offset:49152
	ds_read_b128 v[194:197], v169 offset:50176
	ds_read_b128 v[198:201], v169 offset:51200
	ds_read_b128 v[202:205], v169 offset:52224
	ds_read_b128 v[220:223], v169 offset:53248
	ds_read_b128 v[224:227], v169 offset:54272
	ds_read_b128 v[228:231], v169 offset:55296
	ds_read_b128 v[240:243], v169 offset:56320
	s_or_b32 s56, s55, 0x4000
	s_mov_b32 m0, s16
	s_nop 0
	buffer_load_dwordx4 v166, s[28:31], s56 offen lds
	s_add_i32 s55, s55, 0x84000
	s_mov_b32 m0, s17
	s_nop 0
	buffer_load_dwordx4 v167, s[28:31], s56 offen lds
	s_nop 0
	s_mov_b32 m0, s34
	s_nop 0
	buffer_load_dwordx4 v166, s[28:31], s55 offen lds
	s_nop 0
	s_mov_b32 m0, s40
	s_nop 0
	buffer_load_dwordx4 v167, s[28:31], s55 offen lds
	s_nop 0
	s_mov_b32 m0, s18
	s_nop 0
	buffer_load_dwordx4 v166, s[24:27], s53 offen lds
	s_nop 0
	s_mov_b32 m0, s19
	s_nop 0
	buffer_load_dwordx4 v167, s[24:27], s53 offen lds
	s_waitcnt vmcnt(8)
	s_waitcnt lgkmcnt(0)
	s_barrier
	s_setprio 1
	v_mfma_f32_16x16x32_bf16 v[60:63], v[152:155], v[190:193], v[60:63]
	v_mfma_f32_16x16x32_bf16 v[52:55], v[160:163], v[190:193], v[52:55]
	v_mfma_f32_16x16x32_bf16 v[44:47], v[152:155], v[198:201], v[44:47]
	v_mfma_f32_16x16x32_bf16 v[36:39], v[160:163], v[198:201], v[36:39]
	v_mfma_f32_16x16x32_bf16 v[28:31], v[152:155], v[220:223], v[28:31]
	v_mfma_f32_16x16x32_bf16 v[20:23], v[160:163], v[220:223], v[20:23]
	v_mfma_f32_16x16x32_bf16 v[12:15], v[152:155], v[228:231], v[12:15]
	v_mfma_f32_16x16x32_bf16 v[4:7], v[160:163], v[228:231], v[4:7]
	v_mfma_f32_16x16x32_bf16 v[60:63], v[156:159], v[194:197], v[60:63]
	v_mfma_f32_16x16x32_bf16 v[52:55], v[170:173], v[194:197], v[52:55]
	v_mfma_f32_16x16x32_bf16 v[44:47], v[156:159], v[202:205], v[44:47]
	v_mfma_f32_16x16x32_bf16 v[36:39], v[170:173], v[202:205], v[36:39]
	v_mfma_f32_16x16x32_bf16 v[28:31], v[156:159], v[224:227], v[28:31]
	v_mfma_f32_16x16x32_bf16 v[20:23], v[170:173], v[224:227], v[20:23]
	v_mfma_f32_16x16x32_bf16 v[12:15], v[156:159], v[240:243], v[12:15]
	v_mfma_f32_16x16x32_bf16 v[4:7], v[170:173], v[240:243], v[4:7]
	v_mfma_f32_16x16x32_bf16 v[56:59], v[174:177], v[190:193], v[56:59]
	v_mfma_f32_16x16x32_bf16 v[48:51], v[182:185], v[190:193], v[48:51]
	v_mfma_f32_16x16x32_bf16 v[40:43], v[174:177], v[198:201], v[40:43]
	v_mfma_f32_16x16x32_bf16 v[32:35], v[182:185], v[198:201], v[32:35]
	v_mfma_f32_16x16x32_bf16 v[24:27], v[174:177], v[220:223], v[24:27]
	v_mfma_f32_16x16x32_bf16 v[16:19], v[182:185], v[220:223], v[16:19]
	v_mfma_f32_16x16x32_bf16 v[8:11], v[174:177], v[228:231], v[8:11]
	v_mfma_f32_16x16x32_bf16 v[0:3], v[182:185], v[228:231], v[0:3]
	v_mfma_f32_16x16x32_bf16 v[56:59], v[178:181], v[194:197], v[56:59]
	v_mfma_f32_16x16x32_bf16 v[48:51], v[186:189], v[194:197], v[48:51]
	v_mfma_f32_16x16x32_bf16 v[40:43], v[178:181], v[202:205], v[40:43]
	v_mfma_f32_16x16x32_bf16 v[32:35], v[186:189], v[202:205], v[32:35]
	v_mfma_f32_16x16x32_bf16 v[24:27], v[178:181], v[224:227], v[24:27]
	v_mfma_f32_16x16x32_bf16 v[16:19], v[186:189], v[224:227], v[16:19]
	v_mfma_f32_16x16x32_bf16 v[8:11], v[178:181], v[240:243], v[8:11]
	v_mfma_f32_16x16x32_bf16 v[0:3], v[186:189], v[240:243], v[0:3]
	s_setprio 0
	s_barrier
	s_add_i32 s52, s52, 2
	s_add_i32 s37, s37, 0x8000
	s_add_i32 s51, s51, 0x8000
	s_cmp_gt_u32 s52, 29
	s_cbranch_scc0 .LBB0_795

.Lnb_p6:
	s_add_i32 s11, s8, 0xffea4000
	s_cmpk_eq_i32 s10, 0x54
	s_cselect_b32 s13, s6, s11
	s_cselect_b32 s12, s7, s9
	s_or_b32 s11, s13, 0x4000
	s_mov_b32 m0, s87
	s_nop 0
	buffer_load_dwordx4 v220, s[20:23], s8 offen lds
	s_nop 0
	s_mov_b32 m0, s89
	s_nop 0
	buffer_load_dwordx4 v221, s[20:23], s8 offen lds
	s_waitcnt vmcnt(24)
	s_waitcnt lgkmcnt(0)
	s_barrier
	s_setprio 1
	v_mfma_f32_16x16x32_bf16 v[164:167], v[128:131], v[184:187], 0
	v_mfma_f32_16x16x32_bf16 v[160:163], v[152:155], v[184:187], 0
	v_mfma_f32_16x16x32_bf16 v[136:139], v[128:131], v[192:195], 0
	v_mfma_f32_16x16x32_bf16 v[132:135], v[152:155], v[192:195], 0
	v_mfma_f32_16x16x32_bf16 v[116:119], v[128:131], v[200:203], 0
	v_mfma_f32_16x16x32_bf16 v[112:115], v[152:155], v[200:203], 0
	v_mfma_f32_16x16x32_bf16 v[76:79], v[128:131], v[224:227], 0
	v_mfma_f32_16x16x32_bf16 v[72:75], v[152:155], v[224:227], 0
	v_mfma_f32_16x16x32_bf16 v[164:167], v[140:143], v[188:191], v[164:167]
	v_mfma_f32_16x16x32_bf16 v[160:163], v[156:159], v[188:191], v[160:163]
	v_mfma_f32_16x16x32_bf16 v[136:139], v[140:143], v[196:199], v[136:139]
	v_mfma_f32_16x16x32_bf16 v[132:135], v[156:159], v[196:199], v[132:135]
	v_mfma_f32_16x16x32_bf16 v[116:119], v[140:143], v[204:207], v[116:119]
	v_mfma_f32_16x16x32_bf16 v[112:115], v[156:159], v[204:207], v[112:115]
	v_mfma_f32_16x16x32_bf16 v[76:79], v[140:143], v[228:231], v[76:79]
	v_mfma_f32_16x16x32_bf16 v[72:75], v[156:159], v[228:231], v[72:75]
	v_mfma_f32_16x16x32_bf16 v[148:151], v[168:171], v[184:187], 0
	v_mfma_f32_16x16x32_bf16 v[144:147], v[176:179], v[184:187], 0
	v_mfma_f32_16x16x32_bf16 v[124:127], v[168:171], v[192:195], 0
	v_mfma_f32_16x16x32_bf16 v[120:123], v[176:179], v[192:195], 0
	v_mfma_f32_16x16x32_bf16 v[108:111], v[168:171], v[200:203], 0
	v_mfma_f32_16x16x32_bf16 v[104:107], v[176:179], v[200:203], 0
	v_mfma_f32_16x16x32_bf16 v[68:71], v[168:171], v[224:227], 0
	v_mfma_f32_16x16x32_bf16 v[64:67], v[176:179], v[224:227], 0
	v_mfma_f32_16x16x32_bf16 v[148:151], v[172:175], v[188:191], v[148:151]
	v_mfma_f32_16x16x32_bf16 v[144:147], v[180:183], v[188:191], v[144:147]
	v_mfma_f32_16x16x32_bf16 v[124:127], v[172:175], v[196:199], v[124:127]
	v_mfma_f32_16x16x32_bf16 v[120:123], v[180:183], v[196:199], v[120:123]
	v_mfma_f32_16x16x32_bf16 v[108:111], v[172:175], v[204:207], v[108:111]
	v_mfma_f32_16x16x32_bf16 v[104:107], v[180:183], v[204:207], v[104:107]
	v_mfma_f32_16x16x32_bf16 v[68:71], v[172:175], v[228:231], v[68:71]
	v_mfma_f32_16x16x32_bf16 v[64:67], v[180:183], v[228:231], v[64:67]
	s_setprio 0
	s_barrier
	ds_read_b128 v[184:187], v223 offset:16384
	ds_read_b128 v[188:191], v223 offset:17408
	ds_read_b128 v[192:195], v223 offset:18432
	ds_read_b128 v[196:199], v223 offset:19456
	ds_read_b128 v[200:203], v223 offset:20480
	ds_read_b128 v[204:207], v223 offset:21504
	ds_read_b128 v[224:227], v223 offset:22528
	ds_read_b128 v[228:231], v223 offset:23552
	s_mov_b32 m0, s51
	s_nop 0
	buffer_load_dwordx4 v220, s[52:55], s12 offen lds
	s_add_i32 s14, s12, 0x160000
	s_mov_b32 m0, s74
	s_nop 0
	buffer_load_dwordx4 v221, s[52:55], s12 offen lds
	s_nop 0
	s_mov_b32 m0, s75
	s_nop 0
	buffer_load_dwordx4 v220, s[52:55], s14 offen lds
	s_nop 0
	s_mov_b32 m0, s76
	s_nop 0
	buffer_load_dwordx4 v221, s[52:55], s14 offen lds
	s_nop 0
	s_mov_b32 m0, s31
	s_nop 0
	buffer_load_dwordx4 v220, s[20:23], s13 offen lds
	s_nop 0
	s_mov_b32 m0, s77
	s_nop 0
	buffer_load_dwordx4 v221, s[20:23], s13 offen lds
	s_waitcnt vmcnt(24)
	s_waitcnt lgkmcnt(0)
	s_barrier
	s_setprio 1
	v_mfma_f32_16x16x32_bf16 v[60:63], v[128:131], v[184:187], 0
	v_mfma_f32_16x16x32_bf16 v[56:59], v[152:155], v[184:187], 0
	v_mfma_f32_16x16x32_bf16 v[44:47], v[128:131], v[192:195], 0
	v_mfma_f32_16x16x32_bf16 v[40:43], v[152:155], v[192:195], 0
	v_mfma_f32_16x16x32_bf16 v[28:31], v[128:131], v[200:203], 0
	v_mfma_f32_16x16x32_bf16 v[24:27], v[152:155], v[200:203], 0
	v_mfma_f32_16x16x32_bf16 v[12:15], v[128:131], v[224:227], 0
	v_mfma_f32_16x16x32_bf16 v[8:11], v[152:155], v[224:227], 0
	v_mfma_f32_16x16x32_bf16 v[60:63], v[140:143], v[188:191], v[60:63]
	v_mfma_f32_16x16x32_bf16 v[56:59], v[156:159], v[188:191], v[56:59]
	v_mfma_f32_16x16x32_bf16 v[44:47], v[140:143], v[196:199], v[44:47]
	v_mfma_f32_16x16x32_bf16 v[40:43], v[156:159], v[196:199], v[40:43]
	v_mfma_f32_16x16x32_bf16 v[28:31], v[140:143], v[204:207], v[28:31]
	v_mfma_f32_16x16x32_bf16 v[24:27], v[156:159], v[204:207], v[24:27]
	v_mfma_f32_16x16x32_bf16 v[12:15], v[140:143], v[228:231], v[12:15]
	v_mfma_f32_16x16x32_bf16 v[8:11], v[156:159], v[228:231], v[8:11]
	v_mfma_f32_16x16x32_bf16 v[52:55], v[168:171], v[184:187], 0
	v_mfma_f32_16x16x32_bf16 v[48:51], v[176:179], v[184:187], 0
	v_mfma_f32_16x16x32_bf16 v[36:39], v[168:171], v[192:195], 0
	v_mfma_f32_16x16x32_bf16 v[32:35], v[176:179], v[192:195], 0
	v_mfma_f32_16x16x32_bf16 v[20:23], v[168:171], v[200:203], 0
	v_mfma_f32_16x16x32_bf16 v[16:19], v[176:179], v[200:203], 0
	v_mfma_f32_16x16x32_bf16 v[4:7], v[168:171], v[224:227], 0
	v_mfma_f32_16x16x32_bf16 v[0:3], v[176:179], v[224:227], 0
	v_mfma_f32_16x16x32_bf16 v[52:55], v[172:175], v[188:191], v[52:55]
	v_mfma_f32_16x16x32_bf16 v[48:51], v[180:183], v[188:191], v[48:51]
	v_mfma_f32_16x16x32_bf16 v[36:39], v[172:175], v[196:199], v[36:39]
	v_mfma_f32_16x16x32_bf16 v[32:35], v[180:183], v[196:199], v[32:35]
	v_mfma_f32_16x16x32_bf16 v[20:23], v[172:175], v[204:207], v[20:23]
	v_mfma_f32_16x16x32_bf16 v[16:19], v[180:183], v[204:207], v[16:19]
	v_mfma_f32_16x16x32_bf16 v[4:7], v[172:175], v[228:231], v[4:7]
	v_mfma_f32_16x16x32_bf16 v[0:3], v[180:183], v[228:231], v[0:3]
	s_setprio 0
	s_barrier
	v_add_u32_e32 v156, 0x18000, v222
	v_add_u32_e32 v180, 0x1c000, v222
	ds_read_b128 v[128:131], v156
	ds_read_b128 v[140:143], v156 offset:1024
	ds_read_b128 v[152:155], v156 offset:2048
	ds_read_b128 v[156:159], v156 offset:3072
	ds_read_b128 v[168:171], v180
	ds_read_b128 v[172:175], v180 offset:1024
	ds_read_b128 v[176:179], v180 offset:2048
	ds_read_b128 v[180:183], v180 offset:3072
	ds_read_b128 v[184:187], v223 offset:32768
	ds_read_b128 v[188:191], v223 offset:33792
	ds_read_b128 v[192:195], v223 offset:34816
	ds_read_b128 v[196:199], v223 offset:35840
	ds_read_b128 v[200:203], v223 offset:36864
	ds_read_b128 v[204:207], v223 offset:37888
	ds_read_b128 v[224:227], v223 offset:38912
	ds_read_b128 v[228:231], v223 offset:39936
	s_add_i32 s13, s13, 0x160000
	s_mov_b32 m0, s78
	s_nop 0
	buffer_load_dwordx4 v220, s[20:23], s13 offen lds
	s_nop 0
	s_mov_b32 m0, s79
	s_nop 0
	buffer_load_dwordx4 v221, s[20:23], s13 offen lds
	s_waitcnt vmcnt(8)
	s_waitcnt lgkmcnt(0)
	s_barrier
	s_setprio 1
	v_mfma_f32_16x16x32_bf16 v[164:167], v[128:131], v[184:187], v[164:167]
	v_mfma_f32_16x16x32_bf16 v[160:163], v[152:155], v[184:187], v[160:163]
	v_mfma_f32_16x16x32_bf16 v[136:139], v[128:131], v[192:195], v[136:139]
	v_mfma_f32_16x16x32_bf16 v[132:135], v[152:155], v[192:195], v[132:135]
	v_mfma_f32_16x16x32_bf16 v[116:119], v[128:131], v[200:203], v[116:119]
	v_mfma_f32_16x16x32_bf16 v[112:115], v[152:155], v[200:203], v[112:115]
	v_mfma_f32_16x16x32_bf16 v[76:79], v[128:131], v[224:227], v[76:79]
	v_mfma_f32_16x16x32_bf16 v[72:75], v[152:155], v[224:227], v[72:75]
	v_mfma_f32_16x16x32_bf16 v[164:167], v[140:143], v[188:191], v[164:167]
	v_mfma_f32_16x16x32_bf16 v[160:163], v[156:159], v[188:191], v[160:163]
	v_mfma_f32_16x16x32_bf16 v[136:139], v[140:143], v[196:199], v[136:139]
	v_mfma_f32_16x16x32_bf16 v[132:135], v[156:159], v[196:199], v[132:135]
	v_mfma_f32_16x16x32_bf16 v[116:119], v[140:143], v[204:207], v[116:119]
	v_mfma_f32_16x16x32_bf16 v[112:115], v[156:159], v[204:207], v[112:115]
	v_mfma_f32_16x16x32_bf16 v[76:79], v[140:143], v[228:231], v[76:79]
	v_mfma_f32_16x16x32_bf16 v[72:75], v[156:159], v[228:231], v[72:75]
	v_mfma_f32_16x16x32_bf16 v[148:151], v[168:171], v[184:187], v[148:151]
	v_mfma_f32_16x16x32_bf16 v[144:147], v[176:179], v[184:187], v[144:147]
	v_mfma_f32_16x16x32_bf16 v[124:127], v[168:171], v[192:195], v[124:127]
	v_mfma_f32_16x16x32_bf16 v[120:123], v[176:179], v[192:195], v[120:123]
	v_mfma_f32_16x16x32_bf16 v[108:111], v[168:171], v[200:203], v[108:111]
	v_mfma_f32_16x16x32_bf16 v[104:107], v[176:179], v[200:203], v[104:107]
	v_mfma_f32_16x16x32_bf16 v[68:71], v[168:171], v[224:227], v[68:71]
	v_mfma_f32_16x16x32_bf16 v[64:67], v[176:179], v[224:227], v[64:67]
	v_mfma_f32_16x16x32_bf16 v[148:151], v[172:175], v[188:191], v[148:151]
	v_mfma_f32_16x16x32_bf16 v[144:147], v[180:183], v[188:191], v[144:147]
	v_mfma_f32_16x16x32_bf16 v[124:127], v[172:175], v[196:199], v[124:127]
	v_mfma_f32_16x16x32_bf16 v[120:123], v[180:183], v[196:199], v[120:123]
	v_mfma_f32_16x16x32_bf16 v[108:111], v[172:175], v[204:207], v[108:111]
	v_mfma_f32_16x16x32_bf16 v[104:107], v[180:183], v[204:207], v[104:107]
	v_mfma_f32_16x16x32_bf16 v[68:71], v[172:175], v[228:231], v[68:71]
	v_mfma_f32_16x16x32_bf16 v[64:67], v[180:183], v[228:231], v[64:67]
	s_setprio 0
	s_barrier
	ds_read_b128 v[184:187], v223 offset:49152
	ds_read_b128 v[188:191], v223 offset:50176
	ds_read_b128 v[192:195], v223 offset:51200
	ds_read_b128 v[196:199], v223 offset:52224
	ds_read_b128 v[200:203], v223 offset:53248
	ds_read_b128 v[204:207], v223 offset:54272
	ds_read_b128 v[224:227], v223 offset:55296
	ds_read_b128 v[228:231], v223 offset:56320
	s_or_b32 s13, s12, 0x4000
	s_mov_b32 m0, s34
	s_nop 0
	buffer_load_dwordx4 v220, s[52:55], s13 offen lds
	s_add_i32 s12, s12, 0x164000
	s_mov_b32 m0, s82
	s_nop 0
	buffer_load_dwordx4 v221, s[52:55], s13 offen lds
	s_nop 0
	s_mov_b32 m0, s85
	s_nop 0
	buffer_load_dwordx4 v220, s[52:55], s12 offen lds
	s_nop 0
	s_mov_b32 m0, s86
	s_nop 0
	buffer_load_dwordx4 v221, s[52:55], s12 offen lds
	s_nop 0
	s_mov_b32 m0, s83
	s_nop 0
	buffer_load_dwordx4 v220, s[20:23], s11 offen lds
	s_nop 0
	s_mov_b32 m0, s84
	s_nop 0
	buffer_load_dwordx4 v221, s[20:23], s11 offen lds
	s_waitcnt vmcnt(8)
	s_waitcnt lgkmcnt(0)
	s_barrier
	s_setprio 1
	v_mfma_f32_16x16x32_bf16 v[60:63], v[128:131], v[184:187], v[60:63]
	v_mfma_f32_16x16x32_bf16 v[56:59], v[152:155], v[184:187], v[56:59]
	v_mfma_f32_16x16x32_bf16 v[44:47], v[128:131], v[192:195], v[44:47]
	v_mfma_f32_16x16x32_bf16 v[40:43], v[152:155], v[192:195], v[40:43]
	v_mfma_f32_16x16x32_bf16 v[28:31], v[128:131], v[200:203], v[28:31]
	v_mfma_f32_16x16x32_bf16 v[24:27], v[152:155], v[200:203], v[24:27]
	v_mfma_f32_16x16x32_bf16 v[12:15], v[128:131], v[224:227], v[12:15]
	v_mfma_f32_16x16x32_bf16 v[8:11], v[152:155], v[224:227], v[8:11]
	v_mfma_f32_16x16x32_bf16 v[60:63], v[140:143], v[188:191], v[60:63]
	v_mfma_f32_16x16x32_bf16 v[56:59], v[156:159], v[188:191], v[56:59]
	v_mfma_f32_16x16x32_bf16 v[44:47], v[140:143], v[196:199], v[44:47]
	v_mfma_f32_16x16x32_bf16 v[40:43], v[156:159], v[196:199], v[40:43]
	v_mfma_f32_16x16x32_bf16 v[28:31], v[140:143], v[204:207], v[28:31]
	v_mfma_f32_16x16x32_bf16 v[24:27], v[156:159], v[204:207], v[24:27]
	v_mfma_f32_16x16x32_bf16 v[12:15], v[140:143], v[228:231], v[12:15]
	v_mfma_f32_16x16x32_bf16 v[8:11], v[156:159], v[228:231], v[8:11]
	v_mfma_f32_16x16x32_bf16 v[52:55], v[168:171], v[184:187], v[52:55]
	v_mfma_f32_16x16x32_bf16 v[48:51], v[176:179], v[184:187], v[48:51]
	v_mfma_f32_16x16x32_bf16 v[36:39], v[168:171], v[192:195], v[36:39]
	v_mfma_f32_16x16x32_bf16 v[32:35], v[176:179], v[192:195], v[32:35]
	v_mfma_f32_16x16x32_bf16 v[20:23], v[168:171], v[200:203], v[20:23]
	v_mfma_f32_16x16x32_bf16 v[16:19], v[176:179], v[200:203], v[16:19]
	v_mfma_f32_16x16x32_bf16 v[4:7], v[168:171], v[224:227], v[4:7]
	v_mfma_f32_16x16x32_bf16 v[0:3], v[176:179], v[224:227], v[0:3]
	v_mfma_f32_16x16x32_bf16 v[52:55], v[172:175], v[188:191], v[52:55]
	v_mfma_f32_16x16x32_bf16 v[48:51], v[180:183], v[188:191], v[48:51]
	v_mfma_f32_16x16x32_bf16 v[36:39], v[172:175], v[196:199], v[36:39]
	v_mfma_f32_16x16x32_bf16 v[32:35], v[180:183], v[196:199], v[32:35]
	v_mfma_f32_16x16x32_bf16 v[20:23], v[172:175], v[204:207], v[20:23]
	v_mfma_f32_16x16x32_bf16 v[16:19], v[180:183], v[204:207], v[16:19]
	v_mfma_f32_16x16x32_bf16 v[4:7], v[172:175], v[228:231], v[4:7]
	v_mfma_f32_16x16x32_bf16 v[0:3], v[180:183], v[228:231], v[0:3]
	s_setprio 0
	s_barrier
	s_add_i32 s10, s10, 2
	s_add_i32 s8, s8, 0x8000
	s_add_i32 s9, s9, 0x8000
.LBB0_885:
	v_add_u32_e32 v156, 0x10000, v222
	v_add_u32_e32 v180, 0x14000, v222
	ds_read_b128 v[128:131], v156
	ds_read_b128 v[140:143], v156 offset:1024
	ds_read_b128 v[152:155], v156 offset:2048
	ds_read_b128 v[156:159], v156 offset:3072
	ds_read_b128 v[168:171], v180
	ds_read_b128 v[172:175], v180 offset:1024
	ds_read_b128 v[176:179], v180 offset:2048
	ds_read_b128 v[180:183], v180 offset:3072
	s_add_i32 s11, s8, 0xffea4000
	s_cmpk_eq_i32 s10, 0x54
	s_cselect_b32 s13, s6, s11
	s_cselect_b32 s12, s7, s9
	s_or_b32 s11, s13, 0x4000
	ds_read_b128 v[184:187], v223
	ds_read_b128 v[188:191], v223 offset:1024
	ds_read_b128 v[192:195], v223 offset:2048
	ds_read_b128 v[196:199], v223 offset:3072
	ds_read_b128 v[200:203], v223 offset:4096
	ds_read_b128 v[204:207], v223 offset:5120
	ds_read_b128 v[224:227], v223 offset:6144
	ds_read_b128 v[228:231], v223 offset:7168
	s_mov_b32 m0, s87
	s_nop 0
	buffer_load_dwordx4 v220, s[20:23], s8 offen lds
	s_nop 0
	s_mov_b32 m0, s89
	s_nop 0
	buffer_load_dwordx4 v221, s[20:23], s8 offen lds
	s_waitcnt vmcnt(8)
	s_waitcnt lgkmcnt(0)
	s_barrier
	s_setprio 1
	v_mfma_f32_16x16x32_bf16 v[164:167], v[128:131], v[184:187], v[164:167]
	v_mfma_f32_16x16x32_bf16 v[160:163], v[152:155], v[184:187], v[160:163]
	v_mfma_f32_16x16x32_bf16 v[136:139], v[128:131], v[192:195], v[136:139]
	v_mfma_f32_16x16x32_bf16 v[132:135], v[152:155], v[192:195], v[132:135]
	v_mfma_f32_16x16x32_bf16 v[116:119], v[128:131], v[200:203], v[116:119]
	v_mfma_f32_16x16x32_bf16 v[112:115], v[152:155], v[200:203], v[112:115]
	v_mfma_f32_16x16x32_bf16 v[76:79], v[128:131], v[224:227], v[76:79]
	v_mfma_f32_16x16x32_bf16 v[72:75], v[152:155], v[224:227], v[72:75]
	v_mfma_f32_16x16x32_bf16 v[164:167], v[140:143], v[188:191], v[164:167]
	v_mfma_f32_16x16x32_bf16 v[160:163], v[156:159], v[188:191], v[160:163]
	v_mfma_f32_16x16x32_bf16 v[136:139], v[140:143], v[196:199], v[136:139]
	v_mfma_f32_16x16x32_bf16 v[132:135], v[156:159], v[196:199], v[132:135]
	v_mfma_f32_16x16x32_bf16 v[116:119], v[140:143], v[204:207], v[116:119]
	v_mfma_f32_16x16x32_bf16 v[112:115], v[156:159], v[204:207], v[112:115]
	v_mfma_f32_16x16x32_bf16 v[76:79], v[140:143], v[228:231], v[76:79]
	v_mfma_f32_16x16x32_bf16 v[72:75], v[156:159], v[228:231], v[72:75]
	v_mfma_f32_16x16x32_bf16 v[148:151], v[168:171], v[184:187], v[148:151]
	v_mfma_f32_16x16x32_bf16 v[144:147], v[176:179], v[184:187], v[144:147]
	v_mfma_f32_16x16x32_bf16 v[124:127], v[168:171], v[192:195], v[124:127]
	v_mfma_f32_16x16x32_bf16 v[120:123], v[176:179], v[192:195], v[120:123]
	v_mfma_f32_16x16x32_bf16 v[108:111], v[168:171], v[200:203], v[108:111]
	v_mfma_f32_16x16x32_bf16 v[104:107], v[176:179], v[200:203], v[104:107]
	v_mfma_f32_16x16x32_bf16 v[68:71], v[168:171], v[224:227], v[68:71]
	v_mfma_f32_16x16x32_bf16 v[64:67], v[176:179], v[224:227], v[64:67]
	v_mfma_f32_16x16x32_bf16 v[148:151], v[172:175], v[188:191], v[148:151]
	v_mfma_f32_16x16x32_bf16 v[144:147], v[180:183], v[188:191], v[144:147]
	v_mfma_f32_16x16x32_bf16 v[124:127], v[172:175], v[196:199], v[124:127]
	v_mfma_f32_16x16x32_bf16 v[120:123], v[180:183], v[196:199], v[120:123]
	v_mfma_f32_16x16x32_bf16 v[108:111], v[172:175], v[204:207], v[108:111]
	v_mfma_f32_16x16x32_bf16 v[104:107], v[180:183], v[204:207], v[104:107]
	v_mfma_f32_16x16x32_bf16 v[68:71], v[172:175], v[228:231], v[68:71]
	v_mfma_f32_16x16x32_bf16 v[64:67], v[180:183], v[228:231], v[64:67]
	s_setprio 0
	s_barrier
	ds_read_b128 v[184:187], v223 offset:16384
	ds_read_b128 v[188:191], v223 offset:17408
	ds_read_b128 v[192:195], v223 offset:18432
	ds_read_b128 v[196:199], v223 offset:19456
	ds_read_b128 v[200:203], v223 offset:20480
	ds_read_b128 v[204:207], v223 offset:21504
	ds_read_b128 v[224:227], v223 offset:22528
	ds_read_b128 v[228:231], v223 offset:23552
	s_mov_b32 m0, s51
	s_nop 0
	buffer_load_dwordx4 v220, s[52:55], s12 offen lds
	s_add_i32 s14, s12, 0x160000
	s_mov_b32 m0, s74
	s_nop 0
	buffer_load_dwordx4 v221, s[52:55], s12 offen lds
	s_nop 0
	s_mov_b32 m0, s75
	s_nop 0
	buffer_load_dwordx4 v220, s[52:55], s14 offen lds
	s_nop 0
	s_mov_b32 m0, s76
	s_nop 0
	buffer_load_dwordx4 v221, s[52:55], s14 offen lds
	s_nop 0
	s_mov_b32 m0, s31
	s_nop 0
	buffer_load_dwordx4 v220, s[20:23], s13 offen lds
	s_nop 0
	s_mov_b32 m0, s77
	s_nop 0
	buffer_load_dwordx4 v221, s[20:23], s13 offen lds
	s_waitcnt vmcnt(8)
	s_waitcnt lgkmcnt(0)
	s_barrier
	s_setprio 1
	v_mfma_f32_16x16x32_bf16 v[60:63], v[128:131], v[184:187], v[60:63]
	v_mfma_f32_16x16x32_bf16 v[56:59], v[152:155], v[184:187], v[56:59]
	v_mfma_f32_16x16x32_bf16 v[44:47], v[128:131], v[192:195], v[44:47]
	v_mfma_f32_16x16x32_bf16 v[40:43], v[152:155], v[192:195], v[40:43]
	v_mfma_f32_16x16x32_bf16 v[28:31], v[128:131], v[200:203], v[28:31]
	v_mfma_f32_16x16x32_bf16 v[24:27], v[152:155], v[200:203], v[24:27]
	v_mfma_f32_16x16x32_bf16 v[12:15], v[128:131], v[224:227], v[12:15]
	v_mfma_f32_16x16x32_bf16 v[8:11], v[152:155], v[224:227], v[8:11]
	v_mfma_f32_16x16x32_bf16 v[60:63], v[140:143], v[188:191], v[60:63]
	v_mfma_f32_16x16x32_bf16 v[56:59], v[156:159], v[188:191], v[56:59]
	v_mfma_f32_16x16x32_bf16 v[44:47], v[140:143], v[196:199], v[44:47]
	v_mfma_f32_16x16x32_bf16 v[40:43], v[156:159], v[196:199], v[40:43]
	v_mfma_f32_16x16x32_bf16 v[28:31], v[140:143], v[204:207], v[28:31]
	v_mfma_f32_16x16x32_bf16 v[24:27], v[156:159], v[204:207], v[24:27]
	v_mfma_f32_16x16x32_bf16 v[12:15], v[140:143], v[228:231], v[12:15]
	v_mfma_f32_16x16x32_bf16 v[8:11], v[156:159], v[228:231], v[8:11]
	v_mfma_f32_16x16x32_bf16 v[52:55], v[168:171], v[184:187], v[52:55]
	v_mfma_f32_16x16x32_bf16 v[48:51], v[176:179], v[184:187], v[48:51]
	v_mfma_f32_16x16x32_bf16 v[36:39], v[168:171], v[192:195], v[36:39]
	v_mfma_f32_16x16x32_bf16 v[32:35], v[176:179], v[192:195], v[32:35]
	v_mfma_f32_16x16x32_bf16 v[20:23], v[168:171], v[200:203], v[20:23]
	v_mfma_f32_16x16x32_bf16 v[16:19], v[176:179], v[200:203], v[16:19]
	v_mfma_f32_16x16x32_bf16 v[4:7], v[168:171], v[224:227], v[4:7]
	v_mfma_f32_16x16x32_bf16 v[0:3], v[176:179], v[224:227], v[0:3]
	v_mfma_f32_16x16x32_bf16 v[52:55], v[172:175], v[188:191], v[52:55]
	v_mfma_f32_16x16x32_bf16 v[48:51], v[180:183], v[188:191], v[48:51]
	v_mfma_f32_16x16x32_bf16 v[36:39], v[172:175], v[196:199], v[36:39]
	v_mfma_f32_16x16x32_bf16 v[32:35], v[180:183], v[196:199], v[32:35]
	v_mfma_f32_16x16x32_bf16 v[20:23], v[172:175], v[204:207], v[20:23]
	v_mfma_f32_16x16x32_bf16 v[16:19], v[180:183], v[204:207], v[16:19]
	v_mfma_f32_16x16x32_bf16 v[4:7], v[172:175], v[228:231], v[4:7]
	v_mfma_f32_16x16x32_bf16 v[0:3], v[180:183], v[228:231], v[0:3]
	s_setprio 0
	s_barrier
	v_add_u32_e32 v156, 0x18000, v222
	v_add_u32_e32 v180, 0x1c000, v222
	ds_read_b128 v[128:131], v156
	ds_read_b128 v[140:143], v156 offset:1024
	ds_read_b128 v[152:155], v156 offset:2048
	ds_read_b128 v[156:159], v156 offset:3072
	ds_read_b128 v[168:171], v180
	ds_read_b128 v[172:175], v180 offset:1024
	ds_read_b128 v[176:179], v180 offset:2048
	ds_read_b128 v[180:183], v180 offset:3072
	ds_read_b128 v[184:187], v223 offset:32768
	ds_read_b128 v[188:191], v223 offset:33792
	ds_read_b128 v[192:195], v223 offset:34816
	ds_read_b128 v[196:199], v223 offset:35840
	ds_read_b128 v[200:203], v223 offset:36864
	ds_read_b128 v[204:207], v223 offset:37888
	ds_read_b128 v[224:227], v223 offset:38912
	ds_read_b128 v[228:231], v223 offset:39936
	s_add_i32 s13, s13, 0x160000
	s_mov_b32 m0, s78
	s_nop 0
	buffer_load_dwordx4 v220, s[20:23], s13 offen lds
	s_nop 0
	s_mov_b32 m0, s79
	s_nop 0
	buffer_load_dwordx4 v221, s[20:23], s13 offen lds
	s_waitcnt vmcnt(8)
	s_waitcnt lgkmcnt(0)
	s_barrier
	s_setprio 1
	v_mfma_f32_16x16x32_bf16 v[164:167], v[128:131], v[184:187], v[164:167]
	v_mfma_f32_16x16x32_bf16 v[160:163], v[152:155], v[184:187], v[160:163]
	v_mfma_f32_16x16x32_bf16 v[136:139], v[128:131], v[192:195], v[136:139]
	v_mfma_f32_16x16x32_bf16 v[132:135], v[152:155], v[192:195], v[132:135]
	v_mfma_f32_16x16x32_bf16 v[116:119], v[128:131], v[200:203], v[116:119]
	v_mfma_f32_16x16x32_bf16 v[112:115], v[152:155], v[200:203], v[112:115]
	v_mfma_f32_16x16x32_bf16 v[76:79], v[128:131], v[224:227], v[76:79]
	v_mfma_f32_16x16x32_bf16 v[72:75], v[152:155], v[224:227], v[72:75]
	v_mfma_f32_16x16x32_bf16 v[164:167], v[140:143], v[188:191], v[164:167]
	v_mfma_f32_16x16x32_bf16 v[160:163], v[156:159], v[188:191], v[160:163]
	v_mfma_f32_16x16x32_bf16 v[136:139], v[140:143], v[196:199], v[136:139]
	v_mfma_f32_16x16x32_bf16 v[132:135], v[156:159], v[196:199], v[132:135]
	v_mfma_f32_16x16x32_bf16 v[116:119], v[140:143], v[204:207], v[116:119]
	v_mfma_f32_16x16x32_bf16 v[112:115], v[156:159], v[204:207], v[112:115]
	v_mfma_f32_16x16x32_bf16 v[76:79], v[140:143], v[228:231], v[76:79]
	v_mfma_f32_16x16x32_bf16 v[72:75], v[156:159], v[228:231], v[72:75]
	v_mfma_f32_16x16x32_bf16 v[148:151], v[168:171], v[184:187], v[148:151]
	v_mfma_f32_16x16x32_bf16 v[144:147], v[176:179], v[184:187], v[144:147]
	v_mfma_f32_16x16x32_bf16 v[124:127], v[168:171], v[192:195], v[124:127]
	v_mfma_f32_16x16x32_bf16 v[120:123], v[176:179], v[192:195], v[120:123]
	v_mfma_f32_16x16x32_bf16 v[108:111], v[168:171], v[200:203], v[108:111]
	v_mfma_f32_16x16x32_bf16 v[104:107], v[176:179], v[200:203], v[104:107]
	v_mfma_f32_16x16x32_bf16 v[68:71], v[168:171], v[224:227], v[68:71]
	v_mfma_f32_16x16x32_bf16 v[64:67], v[176:179], v[224:227], v[64:67]
	v_mfma_f32_16x16x32_bf16 v[148:151], v[172:175], v[188:191], v[148:151]
	v_mfma_f32_16x16x32_bf16 v[144:147], v[180:183], v[188:191], v[144:147]
	v_mfma_f32_16x16x32_bf16 v[124:127], v[172:175], v[196:199], v[124:127]
	v_mfma_f32_16x16x32_bf16 v[120:123], v[180:183], v[196:199], v[120:123]
	v_mfma_f32_16x16x32_bf16 v[108:111], v[172:175], v[204:207], v[108:111]
	v_mfma_f32_16x16x32_bf16 v[104:107], v[180:183], v[204:207], v[104:107]
	v_mfma_f32_16x16x32_bf16 v[68:71], v[172:175], v[228:231], v[68:71]
	v_mfma_f32_16x16x32_bf16 v[64:67], v[180:183], v[228:231], v[64:67]
	s_setprio 0
	s_barrier
	ds_read_b128 v[184:187], v223 offset:49152
	ds_read_b128 v[188:191], v223 offset:50176
	ds_read_b128 v[192:195], v223 offset:51200
	ds_read_b128 v[196:199], v223 offset:52224
	ds_read_b128 v[200:203], v223 offset:53248
	ds_read_b128 v[204:207], v223 offset:54272
	ds_read_b128 v[224:227], v223 offset:55296
	ds_read_b128 v[228:231], v223 offset:56320
	s_or_b32 s13, s12, 0x4000
	s_mov_b32 m0, s34
	s_nop 0
	buffer_load_dwordx4 v220, s[52:55], s13 offen lds
	s_add_i32 s12, s12, 0x164000
	s_mov_b32 m0, s82
	s_nop 0
	buffer_load_dwordx4 v221, s[52:55], s13 offen lds
	s_nop 0
	s_mov_b32 m0, s85
	s_nop 0
	buffer_load_dwordx4 v220, s[52:55], s12 offen lds
	s_nop 0
	s_mov_b32 m0, s86
	s_nop 0
	buffer_load_dwordx4 v221, s[52:55], s12 offen lds
	s_nop 0
	s_mov_b32 m0, s83
	s_nop 0
	buffer_load_dwordx4 v220, s[20:23], s11 offen lds
	s_nop 0
	s_mov_b32 m0, s84
	s_nop 0
	buffer_load_dwordx4 v221, s[20:23], s11 offen lds
	s_waitcnt vmcnt(8)
	s_waitcnt lgkmcnt(0)
	s_barrier
	s_setprio 1
	v_mfma_f32_16x16x32_bf16 v[60:63], v[128:131], v[184:187], v[60:63]
	v_mfma_f32_16x16x32_bf16 v[56:59], v[152:155], v[184:187], v[56:59]
	v_mfma_f32_16x16x32_bf16 v[44:47], v[128:131], v[192:195], v[44:47]
	v_mfma_f32_16x16x32_bf16 v[40:43], v[152:155], v[192:195], v[40:43]
	v_mfma_f32_16x16x32_bf16 v[28:31], v[128:131], v[200:203], v[28:31]
	v_mfma_f32_16x16x32_bf16 v[24:27], v[152:155], v[200:203], v[24:27]
	v_mfma_f32_16x16x32_bf16 v[12:15], v[128:131], v[224:227], v[12:15]
	v_mfma_f32_16x16x32_bf16 v[8:11], v[152:155], v[224:227], v[8:11]
	v_mfma_f32_16x16x32_bf16 v[60:63], v[140:143], v[188:191], v[60:63]
	v_mfma_f32_16x16x32_bf16 v[56:59], v[156:159], v[188:191], v[56:59]
	v_mfma_f32_16x16x32_bf16 v[44:47], v[140:143], v[196:199], v[44:47]
	v_mfma_f32_16x16x32_bf16 v[40:43], v[156:159], v[196:199], v[40:43]
	v_mfma_f32_16x16x32_bf16 v[28:31], v[140:143], v[204:207], v[28:31]
	v_mfma_f32_16x16x32_bf16 v[24:27], v[156:159], v[204:207], v[24:27]
	v_mfma_f32_16x16x32_bf16 v[12:15], v[140:143], v[228:231], v[12:15]
	v_mfma_f32_16x16x32_bf16 v[8:11], v[156:159], v[228:231], v[8:11]
	v_mfma_f32_16x16x32_bf16 v[52:55], v[168:171], v[184:187], v[52:55]
	v_mfma_f32_16x16x32_bf16 v[48:51], v[176:179], v[184:187], v[48:51]
	v_mfma_f32_16x16x32_bf16 v[36:39], v[168:171], v[192:195], v[36:39]
	v_mfma_f32_16x16x32_bf16 v[32:35], v[176:179], v[192:195], v[32:35]
	v_mfma_f32_16x16x32_bf16 v[20:23], v[168:171], v[200:203], v[20:23]
	v_mfma_f32_16x16x32_bf16 v[16:19], v[176:179], v[200:203], v[16:19]
	v_mfma_f32_16x16x32_bf16 v[4:7], v[168:171], v[224:227], v[4:7]
	v_mfma_f32_16x16x32_bf16 v[0:3], v[176:179], v[224:227], v[0:3]
	v_mfma_f32_16x16x32_bf16 v[52:55], v[172:175], v[188:191], v[52:55]
	v_mfma_f32_16x16x32_bf16 v[48:51], v[180:183], v[188:191], v[48:51]
	v_mfma_f32_16x16x32_bf16 v[36:39], v[172:175], v[196:199], v[36:39]
	v_mfma_f32_16x16x32_bf16 v[32:35], v[180:183], v[196:199], v[32:35]
	v_mfma_f32_16x16x32_bf16 v[20:23], v[172:175], v[204:207], v[20:23]
	v_mfma_f32_16x16x32_bf16 v[16:19], v[180:183], v[204:207], v[16:19]
	v_mfma_f32_16x16x32_bf16 v[4:7], v[172:175], v[228:231], v[4:7]
	v_mfma_f32_16x16x32_bf16 v[0:3], v[180:183], v[228:231], v[0:3]
	s_setprio 0
	s_barrier
	s_add_i32 s10, s10, 2
	s_add_i32 s8, s8, 0x8000
	s_add_i32 s9, s9, 0x8000
	s_cmpk_gt_u32 s10, 0x55
	s_cbranch_scc0 .LBB0_885
